# K-loop back edge rotated (guide 7.11): counter/pointer/exit test and loop-back branch moved in front of the iteration's last barrier, barrier is the loop head
# baseline (speedup 1.0000x reference)
; #define PG8_MMA(ai, bj, At, Bt) do { __builtin_amdgcn_s_setprio(1); _Pragma("unroll") for (int m = 0; m < 4; ++m) _Pragma("unroll") for (int n = 0; n < 2; ++n) _Pragma("unroll") for (int k = 0; k < 2; ++k) \
;         acc[ai][bj][m][n] = __builtin_amdgcn_mfma_f32_16x16x32_bf16(Bt[n][k], At[m][k], acc[ai][bj][m][n], 0, 0, 0); __builtin_amdgcn_s_setprio(0); } while (0)
; #define PG8_WAIT_V(n) asm volatile("s_waitcnt vmcnt(" #n ")" ::: "memory")
; #define PG8_WAIT_L(n) asm volatile("s_waitcnt lgkmcnt(" #n ")" ::: "memory")
; #define PG8_BAR __builtin_amdgcn_s_barrier()
; #define PG8_SCHED __builtin_amdgcn_sched_barrier(0)
; template <class Epi, class Sched, bool ALIGN_EPI = false, bool SP2 = false>
; __device__ __forceinline__ void gemm_phase(PG8_LAS unsigned char* lds, const Gemm g, const Sched& S, const Epi& E) {
;     ...
;             PG8_WAIT_V(8); PG8_WAIT_L(0); PG8_BAR; PG8_MMA(1, 0, At, B0); PG8_MMA(1, 1, At, B1); PG8_BAR; PG8_SCHED;
.Lrb1:
	s_barrier

; #define PG8_STAGE(bufoff, gbase, voff) do { _Pragma("unroll") for (int _i = 0; _i < 2; ++_i) \
;         __builtin_amdgcn_global_load_lds((const unsigned*)((const char*)(gbase) + (voff)[_i]), (PG8_LAS unsigned*)(lds + (bufoff) + ldsw + _i * 8192), 16, 0, 0); } while (0)
; #define PG8_LDA(dst, b, h) do { _Pragma("unroll") for (int m = 0; m < 4; ++m) _Pragma("unroll") for (int k = 0; k < 2; ++k) dst[m][k] = *(const PG8_LAS bf16x8*)(lds + PG8_SA(b, h) + aoff + m * 2048 + k * 1024); } while (0)
; #define PG8_LDB(dst, b, h) do { _Pragma("unroll") for (int n = 0; n < 2; ++n) _Pragma("unroll") for (int k = 0; k < 2; ++k) dst[n][k] = *(const PG8_LAS bf16x8*)(lds + PG8_SB(b, h) + boff + n * 2048 + k * 1024); } while (0)
; #define PG8_MMA(ai, bj, At, Bt) do { __builtin_amdgcn_s_setprio(1); _Pragma("unroll") for (int m = 0; m < 4; ++m) _Pragma("unroll") for (int n = 0; n < 2; ++n) _Pragma("unroll") for (int k = 0; k < 2; ++k) \
;         acc[ai][bj][m][n] = __builtin_amdgcn_mfma_f32_16x16x32_bf16(Bt[n][k], At[m][k], acc[ai][bj][m][n], 0, 0, 0); __builtin_amdgcn_s_setprio(0); } while (0)
; #define PG8_WAIT_V(n) asm volatile("s_waitcnt vmcnt(" #n ")" ::: "memory")
; #define PG8_WAIT_L(n) asm volatile("s_waitcnt lgkmcnt(" #n ")" ::: "memory")
; #define PG8_BAR __builtin_amdgcn_s_barrier()
; #define PG8_SCHED __builtin_amdgcn_sched_barrier(0)
; template <class Epi, class Sched, bool ALIGN_EPI = false, bool SP2 = false>
; __device__ __forceinline__ void gemm_phase(PG8_LAS unsigned char* lds, const Gemm g, const Sched& S, const Epi& E) {
;     ...
;             PG8_LDB(B0, 1, 0); PG8_LDB(B1, 1, 1); PG8_SCHED; PG8_LDA(At, 1, 0); PG8_STAGE(PG8_SA(0, 1), a2 + hstep, voffA);
;             PG8_WAIT_V(8); PG8_WAIT_L(0); PG8_BAR; PG8_MMA(0, 0, At, B0); PG8_MMA(0, 1, At, B1); PG8_BAR; PG8_SCHED;
.Lpz1_mid:
	s_add_i32 s55, 0, 0x18000
	v_add_u32_e32 v138, s55, v149
	s_add_i32 s56, 0, 0x1c000
	ds_read_b128 v[154:157], v138
	ds_read_b128 v[158:161], v138 offset:1024
	ds_read_b128 v[162:165], v138 offset:2048
	ds_read_b128 v[166:169], v138 offset:3072
	v_add_u32_e32 v138, s56, v149
	ds_read_b128 v[170:173], v138
	ds_read_b128 v[174:177], v138 offset:1024
	ds_read_b128 v[178:181], v138 offset:2048
	ds_read_b128 v[182:185], v138 offset:3072
	s_add_u32 s26, s26, 0x40000
	s_addc_u32 s27, s27, 0
	s_mov_b32 m0, s39
	v_lshl_add_u64 v[228:229], s[26:27], 0, v[136:137]
	ds_read_b128 v[186:189], v152 offset:32768
	ds_read_b128 v[190:193], v152 offset:33792
	ds_read_b128 v[194:197], v152 offset:34816
	ds_read_b128 v[198:201], v152 offset:35840
	ds_read_b128 v[202:205], v152 offset:36864
	ds_read_b128 v[206:209], v152 offset:37888
	ds_read_b128 v[210:213], v152 offset:38912
	ds_read_b128 v[214:217], v152 offset:39936
	global_load_lds_dwordx4 v[228:229], off
	v_lshl_add_u64 v[228:229], s[26:27], 0, v[132:133]
	s_mov_b32 m0, s40
	s_nop 0
	global_load_lds_dwordx4 v[228:229], off
	s_waitcnt vmcnt(8)
	s_waitcnt lgkmcnt(0)
	s_barrier
	s_setprio 1
	s_waitcnt lgkmcnt(0)
	v_mfma_f32_16x16x32_bf16 v[126:129], v[154:157], v[186:189], v[126:129]
	v_mfma_f32_16x16x32_bf16 v[122:125], v[162:165], v[186:189], v[122:125]
	v_mfma_f32_16x16x32_bf16 v[110:113], v[154:157], v[194:197], v[110:113]
	v_mfma_f32_16x16x32_bf16 v[106:109], v[162:165], v[194:197], v[106:109]
	v_mfma_f32_16x16x32_bf16 v[94:97], v[154:157], v[202:205], v[94:97]
	v_mfma_f32_16x16x32_bf16 v[90:93], v[162:165], v[202:205], v[90:93]
	v_mfma_f32_16x16x32_bf16 v[78:81], v[154:157], v[210:213], v[78:81]
	v_mfma_f32_16x16x32_bf16 v[74:77], v[162:165], v[210:213], v[74:77]
	v_mfma_f32_16x16x32_bf16 v[126:129], v[158:161], v[190:193], v[126:129]
	v_mfma_f32_16x16x32_bf16 v[122:125], v[166:169], v[190:193], v[122:125]
	v_mfma_f32_16x16x32_bf16 v[110:113], v[158:161], v[198:201], v[110:113]
	v_mfma_f32_16x16x32_bf16 v[106:109], v[166:169], v[198:201], v[106:109]
	v_mfma_f32_16x16x32_bf16 v[94:97], v[158:161], v[206:209], v[94:97]
	v_mfma_f32_16x16x32_bf16 v[90:93], v[166:169], v[206:209], v[90:93]
	v_mfma_f32_16x16x32_bf16 v[78:81], v[158:161], v[214:217], v[78:81]
	v_mfma_f32_16x16x32_bf16 v[74:77], v[166:169], v[214:217], v[74:77]
	s_setprio 0
	s_setprio 1
	v_mfma_f32_16x16x32_bf16 v[118:121], v[170:173], v[186:189], v[118:121]
	v_mfma_f32_16x16x32_bf16 v[114:117], v[178:181], v[186:189], v[114:117]
	v_mfma_f32_16x16x32_bf16 v[102:105], v[170:173], v[194:197], v[102:105]
	v_mfma_f32_16x16x32_bf16 v[98:101], v[178:181], v[194:197], v[98:101]
	v_mfma_f32_16x16x32_bf16 v[86:89], v[170:173], v[202:205], v[86:89]
	v_mfma_f32_16x16x32_bf16 v[82:85], v[178:181], v[202:205], v[82:85]
	v_mfma_f32_16x16x32_bf16 v[70:73], v[170:173], v[210:213], v[70:73]
	v_mfma_f32_16x16x32_bf16 v[66:69], v[178:181], v[210:213], v[66:69]
	v_mfma_f32_16x16x32_bf16 v[118:121], v[174:177], v[190:193], v[118:121]
	v_mfma_f32_16x16x32_bf16 v[114:117], v[182:185], v[190:193], v[114:117]
	v_mfma_f32_16x16x32_bf16 v[102:105], v[174:177], v[198:201], v[102:105]
	v_mfma_f32_16x16x32_bf16 v[98:101], v[182:185], v[198:201], v[98:101]
	v_mfma_f32_16x16x32_bf16 v[86:89], v[174:177], v[206:209], v[86:89]
	v_mfma_f32_16x16x32_bf16 v[82:85], v[182:185], v[206:209], v[82:85]
	v_mfma_f32_16x16x32_bf16 v[70:73], v[174:177], v[214:217], v[70:73]
	v_mfma_f32_16x16x32_bf16 v[66:69], v[182:185], v[214:217], v[66:69]
	s_setprio 0
	s_barrier
; #define PG8_STAGE(bufoff, gbase, voff) do { _Pragma("unroll") for (int _i = 0; _i < 2; ++_i) \
;         __builtin_amdgcn_global_load_lds((const unsigned*)((const char*)(gbase) + (voff)[_i]), (PG8_LAS unsigned*)(lds + (bufoff) + ldsw + _i * 8192), 16, 0, 0); } while (0)
; #define PG8_LDA(dst, b, h) do { _Pragma("unroll") for (int m = 0; m < 4; ++m) _Pragma("unroll") for (int k = 0; k < 2; ++k) dst[m][k] = *(const PG8_LAS bf16x8*)(lds + PG8_SA(b, h) + aoff + m * 2048 + k * 1024); } while (0)
; #define PG8_MMA(ai, bj, At, Bt) do { __builtin_amdgcn_s_setprio(1); _Pragma("unroll") for (int m = 0; m < 4; ++m) _Pragma("unroll") for (int n = 0; n < 2; ++n) _Pragma("unroll") for (int k = 0; k < 2; ++k) \
;         acc[ai][bj][m][n] = __builtin_amdgcn_mfma_f32_16x16x32_bf16(Bt[n][k], At[m][k], acc[ai][bj][m][n], 0, 0, 0); __builtin_amdgcn_s_setprio(0); } while (0)
; #define PG8_WAIT_V(n) asm volatile("s_waitcnt vmcnt(" #n ")" ::: "memory")
; #define PG8_WAIT_L(n) asm volatile("s_waitcnt lgkmcnt(" #n ")" ::: "memory")
; #define PG8_BAR __builtin_amdgcn_s_barrier()
; #define PG8_SCHED __builtin_amdgcn_sched_barrier(0)
; template <class Epi, class Sched, bool ALIGN_EPI = false, bool SP2 = false>
; __device__ __forceinline__ void gemm_phase(PG8_LAS unsigned char* lds, const Gemm g, const Sched& S, const Epi& E) {
;     ...
;         for (int t = 0; t < nt; t += 2) {
;     ...
;             PG8_LDA(At, 1, 1); PG8_STAGE(PG8_SB(1, 0), b3, voffB); PG8_STAGE(PG8_SB(1, 1), b3 + hstep, voffB); PG8_STAGE(PG8_SA(1, 0), a3, voffA);
;             PG8_WAIT_V(8); PG8_WAIT_L(0); PG8_BAR; PG8_MMA(1, 0, At, B0); PG8_MMA(1, 1, At, B1); PG8_BAR; PG8_SCHED;
	s_add_i32 s26, s55, s34
	v_lshl_add_u64 v[218:219], v[218:219], 0, s[8:9]
	s_mov_b32 m0, s26
	ds_read_b128 v[186:189], v152 offset:49152
	ds_read_b128 v[190:193], v152 offset:50176
	ds_read_b128 v[194:197], v152 offset:51200
	ds_read_b128 v[198:201], v152 offset:52224
	ds_read_b128 v[202:205], v152 offset:53248
	ds_read_b128 v[206:209], v152 offset:54272
	ds_read_b128 v[210:213], v152 offset:55296
	ds_read_b128 v[214:217], v152 offset:56320
	global_load_lds_dwordx4 v[218:219], off
	s_add_i32 m0, s26, 0x2000
	s_add_u32 s24, s24, 0x40080
	v_lshl_add_u64 v[218:219], v[222:223], 0, s[8:9]
	s_addc_u32 s25, s25, 0
	s_add_i32 s26, s56, s34
	global_load_lds_dwordx4 v[218:219], off
	v_lshl_add_u64 v[218:219], s[24:25], 0, v[134:135]
	s_mov_b32 m0, s26
	s_nop 0
	global_load_lds_dwordx4 v[218:219], off
	v_lshl_add_u64 v[218:219], s[24:25], 0, v[130:131]
	s_add_i32 m0, s26, 0x2000
	s_nop 0
	global_load_lds_dwordx4 v[218:219], off
	v_lshl_add_u64 v[218:219], v[224:225], 0, s[8:9]
	s_mov_b32 m0, s42
	s_nop 0
	global_load_lds_dwordx4 v[218:219], off
	v_lshl_add_u64 v[218:219], v[226:227], 0, s[8:9]
	s_mov_b32 m0, s43
	s_nop 0
	global_load_lds_dwordx4 v[218:219], off
	s_waitcnt vmcnt(8)
	s_waitcnt lgkmcnt(0)
	s_barrier
	s_setprio 1
	s_waitcnt lgkmcnt(0)
	v_mfma_f32_16x16x32_bf16 v[62:65], v[154:157], v[186:189], v[62:65]
	v_mfma_f32_16x16x32_bf16 v[58:61], v[162:165], v[186:189], v[58:61]
	v_mfma_f32_16x16x32_bf16 v[46:49], v[154:157], v[194:197], v[46:49]
	v_mfma_f32_16x16x32_bf16 v[42:45], v[162:165], v[194:197], v[42:45]
	v_mfma_f32_16x16x32_bf16 v[30:33], v[154:157], v[202:205], v[30:33]
	v_mfma_f32_16x16x32_bf16 v[26:29], v[162:165], v[202:205], v[26:29]
	v_mfma_f32_16x16x32_bf16 v[14:17], v[154:157], v[210:213], v[14:17]
	v_mfma_f32_16x16x32_bf16 v[10:13], v[162:165], v[210:213], v[10:13]
	v_mfma_f32_16x16x32_bf16 v[62:65], v[158:161], v[190:193], v[62:65]
	v_mfma_f32_16x16x32_bf16 v[58:61], v[166:169], v[190:193], v[58:61]
	v_mfma_f32_16x16x32_bf16 v[46:49], v[158:161], v[198:201], v[46:49]
	v_mfma_f32_16x16x32_bf16 v[42:45], v[166:169], v[198:201], v[42:45]
	v_mfma_f32_16x16x32_bf16 v[30:33], v[158:161], v[206:209], v[30:33]
	v_mfma_f32_16x16x32_bf16 v[26:29], v[166:169], v[206:209], v[26:29]
	v_mfma_f32_16x16x32_bf16 v[14:17], v[158:161], v[214:217], v[14:17]
	v_mfma_f32_16x16x32_bf16 v[10:13], v[166:169], v[214:217], v[10:13]
	s_setprio 0
	s_setprio 1
	v_mfma_f32_16x16x32_bf16 v[54:57], v[170:173], v[186:189], v[54:57]
	v_mfma_f32_16x16x32_bf16 v[50:53], v[178:181], v[186:189], v[50:53]
	v_mfma_f32_16x16x32_bf16 v[38:41], v[170:173], v[194:197], v[38:41]
	v_mfma_f32_16x16x32_bf16 v[34:37], v[178:181], v[194:197], v[34:37]
	v_mfma_f32_16x16x32_bf16 v[22:25], v[170:173], v[202:205], v[22:25]
	v_mfma_f32_16x16x32_bf16 v[18:21], v[178:181], v[202:205], v[18:21]
	v_mfma_f32_16x16x32_bf16 v[6:9], v[170:173], v[210:213], v[6:9]
	v_mfma_f32_16x16x32_bf16 v[2:5], v[178:181], v[210:213], v[2:5]
	v_mfma_f32_16x16x32_bf16 v[54:57], v[174:177], v[190:193], v[54:57]
	v_mfma_f32_16x16x32_bf16 v[50:53], v[182:185], v[190:193], v[50:53]
	v_mfma_f32_16x16x32_bf16 v[38:41], v[174:177], v[198:201], v[38:41]
	v_mfma_f32_16x16x32_bf16 v[34:37], v[182:185], v[198:201], v[34:37]
	v_mfma_f32_16x16x32_bf16 v[22:25], v[174:177], v[206:209], v[22:25]
	v_mfma_f32_16x16x32_bf16 v[18:21], v[182:185], v[206:209], v[18:21]
	v_mfma_f32_16x16x32_bf16 v[6:9], v[174:177], v[214:217], v[6:9]
	v_mfma_f32_16x16x32_bf16 v[2:5], v[182:185], v[214:217], v[2:5]
	s_setprio 0
	s_add_i32 s54, s54, 2
	s_add_u32 s22, s22, 0x100
	s_addc_u32 s23, s23, 0
	s_add_u32 s52, s52, 0x100
	s_addc_u32 s53, s53, 0
	s_cmp_gt_u32 s54, 13
	s_cbranch_scc0 .Lrb1
	s_barrier
	s_and_b64 vcc, exec, s[10:11]
	s_cbranch_vccz .LBB0_211
	s_barrier

; #define PG8_STAGE(bufoff, gbase, voff) do { _Pragma("unroll") for (int _i = 0; _i < 2; ++_i) \
;         __builtin_amdgcn_global_load_lds((const unsigned*)((const char*)(gbase) + (voff)[_i]), (PG8_LAS unsigned*)(lds + (bufoff) + ldsw + _i * 8192), 16, 0, 0); } while (0)
; #define PG8_LDA(dst, b, h) do { _Pragma("unroll") for (int m = 0; m < 4; ++m) _Pragma("unroll") for (int k = 0; k < 2; ++k) dst[m][k] = *(const PG8_LAS bf16x8*)(lds + PG8_SA(b, h) + aoff + m * 2048 + k * 1024); } while (0)
; #define PG8_LDB(dst, b, h) do { _Pragma("unroll") for (int n = 0; n < 2; ++n) _Pragma("unroll") for (int k = 0; k < 2; ++k) dst[n][k] = *(const PG8_LAS bf16x8*)(lds + PG8_SB(b, h) + boff + n * 2048 + k * 1024); } while (0)
; #define PG8_MMA(ai, bj, At, Bt) do { __builtin_amdgcn_s_setprio(1); _Pragma("unroll") for (int m = 0; m < 4; ++m) _Pragma("unroll") for (int n = 0; n < 2; ++n) _Pragma("unroll") for (int k = 0; k < 2; ++k) \
;         acc[ai][bj][m][n] = __builtin_amdgcn_mfma_f32_16x16x32_bf16(Bt[n][k], At[m][k], acc[ai][bj][m][n], 0, 0, 0); __builtin_amdgcn_s_setprio(0); } while (0)
; #define PG8_WAIT_V(n) asm volatile("s_waitcnt vmcnt(" #n ")" ::: "memory")
; #define PG8_WAIT_L(n) asm volatile("s_waitcnt lgkmcnt(" #n ")" ::: "memory")
; #define PG8_BAR __builtin_amdgcn_s_barrier()
; #define PG8_SCHED __builtin_amdgcn_sched_barrier(0)
; template <class Epi, class Sched, bool ALIGN_EPI = false, bool SP2 = false>
; __device__ __forceinline__ void gemm_phase(PG8_LAS unsigned char* lds, const Gemm g, const Sched& S, const Epi& E) {
;     ...
;             PG8_LDB(B0, 1, 0); PG8_LDB(B1, 1, 1); PG8_SCHED; PG8_LDA(At, 1, 0); PG8_STAGE(PG8_SA(0, 1), a2 + hstep, voffA);
;             PG8_WAIT_V(8); PG8_WAIT_L(0); PG8_BAR; PG8_MMA(0, 0, At, B0); PG8_MMA(0, 1, At, B1); PG8_BAR; PG8_SCHED;
.Lpz2_mid:
	s_add_i32 s42, 0, 0x18000
	s_add_i32 s43, 0, 0x1c000
	v_add_u32_e32 v142, s42, v222
	v_add_u32_e32 v154, s43, v222
	ds_read_b128 v[130:133], v142
	ds_read_b128 v[134:137], v142 offset:1024
	ds_read_b128 v[138:141], v142 offset:2048
	ds_read_b128 v[142:145], v142 offset:3072
	ds_read_b128 v[164:167], v154
	ds_read_b128 v[168:171], v154 offset:1024
	ds_read_b128 v[172:175], v154 offset:2048
	ds_read_b128 v[176:179], v154 offset:3072
	s_add_u32 s4, s36, 0xb0000
	s_addc_u32 s5, s37, 0
	s_mov_b32 m0, s53
	v_lshl_add_u64 v[216:217], s[4:5], 0, v[146:147]
	ds_read_b128 v[180:183], v225 offset:32768
	ds_read_b128 v[184:187], v225 offset:33792
	ds_read_b128 v[188:191], v225 offset:34816
	ds_read_b128 v[192:195], v225 offset:35840
	ds_read_b128 v[196:199], v225 offset:36864
	ds_read_b128 v[200:203], v225 offset:37888
	ds_read_b128 v[204:207], v225 offset:38912
	ds_read_b128 v[208:211], v225 offset:39936
	global_load_lds_dwordx4 v[216:217], off
	v_lshl_add_u64 v[216:217], s[4:5], 0, v[150:151]
	s_mov_b32 m0, s54
	s_nop 0
	global_load_lds_dwordx4 v[216:217], off
	s_waitcnt vmcnt(8)
	s_waitcnt lgkmcnt(0)
	s_barrier
	s_setprio 1
	s_waitcnt lgkmcnt(0)
	v_mfma_f32_16x16x32_bf16 v[126:129], v[130:133], v[180:183], v[126:129]
	v_mfma_f32_16x16x32_bf16 v[122:125], v[138:141], v[180:183], v[122:125]
	v_mfma_f32_16x16x32_bf16 v[110:113], v[130:133], v[188:191], v[110:113]
	v_mfma_f32_16x16x32_bf16 v[106:109], v[138:141], v[188:191], v[106:109]
	v_mfma_f32_16x16x32_bf16 v[94:97], v[130:133], v[196:199], v[94:97]
	v_mfma_f32_16x16x32_bf16 v[90:93], v[138:141], v[196:199], v[90:93]
	v_mfma_f32_16x16x32_bf16 v[78:81], v[130:133], v[204:207], v[78:81]
	v_mfma_f32_16x16x32_bf16 v[74:77], v[138:141], v[204:207], v[74:77]
	v_mfma_f32_16x16x32_bf16 v[126:129], v[134:137], v[184:187], v[126:129]
	v_mfma_f32_16x16x32_bf16 v[122:125], v[142:145], v[184:187], v[122:125]
	v_mfma_f32_16x16x32_bf16 v[110:113], v[134:137], v[192:195], v[110:113]
	v_mfma_f32_16x16x32_bf16 v[106:109], v[142:145], v[192:195], v[106:109]
	v_mfma_f32_16x16x32_bf16 v[94:97], v[134:137], v[200:203], v[94:97]
	v_mfma_f32_16x16x32_bf16 v[90:93], v[142:145], v[200:203], v[90:93]
	v_mfma_f32_16x16x32_bf16 v[78:81], v[134:137], v[208:211], v[78:81]
	v_mfma_f32_16x16x32_bf16 v[74:77], v[142:145], v[208:211], v[74:77]
	s_setprio 0
	s_setprio 1
	v_mfma_f32_16x16x32_bf16 v[118:121], v[164:167], v[180:183], v[118:121]
	v_mfma_f32_16x16x32_bf16 v[114:117], v[172:175], v[180:183], v[114:117]
	v_mfma_f32_16x16x32_bf16 v[102:105], v[164:167], v[188:191], v[102:105]
	v_mfma_f32_16x16x32_bf16 v[98:101], v[172:175], v[188:191], v[98:101]
	v_mfma_f32_16x16x32_bf16 v[86:89], v[164:167], v[196:199], v[86:89]
	v_mfma_f32_16x16x32_bf16 v[82:85], v[172:175], v[196:199], v[82:85]
	v_mfma_f32_16x16x32_bf16 v[70:73], v[164:167], v[204:207], v[70:73]
	v_mfma_f32_16x16x32_bf16 v[66:69], v[172:175], v[204:207], v[66:69]
	v_mfma_f32_16x16x32_bf16 v[118:121], v[168:171], v[184:187], v[118:121]
	v_mfma_f32_16x16x32_bf16 v[114:117], v[176:179], v[184:187], v[114:117]
	v_mfma_f32_16x16x32_bf16 v[102:105], v[168:171], v[192:195], v[102:105]
	v_mfma_f32_16x16x32_bf16 v[98:101], v[176:179], v[192:195], v[98:101]
	v_mfma_f32_16x16x32_bf16 v[86:89], v[168:171], v[200:203], v[86:89]
	v_mfma_f32_16x16x32_bf16 v[82:85], v[176:179], v[200:203], v[82:85]
	v_mfma_f32_16x16x32_bf16 v[70:73], v[168:171], v[208:211], v[70:73]
	v_mfma_f32_16x16x32_bf16 v[66:69], v[176:179], v[208:211], v[66:69]
	s_setprio 0
	s_barrier
; #define PG8_STAGE(bufoff, gbase, voff) do { _Pragma("unroll") for (int _i = 0; _i < 2; ++_i) \
;         __builtin_amdgcn_global_load_lds((const unsigned*)((const char*)(gbase) + (voff)[_i]), (PG8_LAS unsigned*)(lds + (bufoff) + ldsw + _i * 8192), 16, 0, 0); } while (0)
; #define PG8_LDA(dst, b, h) do { _Pragma("unroll") for (int m = 0; m < 4; ++m) _Pragma("unroll") for (int k = 0; k < 2; ++k) dst[m][k] = *(const PG8_LAS bf16x8*)(lds + PG8_SA(b, h) + aoff + m * 2048 + k * 1024); } while (0)
; #define PG8_MMA(ai, bj, At, Bt) do { __builtin_amdgcn_s_setprio(1); _Pragma("unroll") for (int m = 0; m < 4; ++m) _Pragma("unroll") for (int n = 0; n < 2; ++n) _Pragma("unroll") for (int k = 0; k < 2; ++k) \
;         acc[ai][bj][m][n] = __builtin_amdgcn_mfma_f32_16x16x32_bf16(Bt[n][k], At[m][k], acc[ai][bj][m][n], 0, 0, 0); __builtin_amdgcn_s_setprio(0); } while (0)
; #define PG8_WAIT_V(n) asm volatile("s_waitcnt vmcnt(" #n ")" ::: "memory")
; #define PG8_WAIT_L(n) asm volatile("s_waitcnt lgkmcnt(" #n ")" ::: "memory")
; #define PG8_BAR __builtin_amdgcn_s_barrier()
; #define PG8_SCHED __builtin_amdgcn_sched_barrier(0)
; template <class Epi, class Sched, bool ALIGN_EPI = false, bool SP2 = false>
; __device__ __forceinline__ void gemm_phase(PG8_LAS unsigned char* lds, const Gemm g, const Sched& S, const Epi& E) {
;     ...
;         for (int t = 0; t < nt; t += 2) {
;     ...
;             PG8_LDA(At, 1, 1); PG8_STAGE(PG8_SB(1, 0), b3, voffB); PG8_STAGE(PG8_SB(1, 1), b3 + hstep, voffB); PG8_STAGE(PG8_SA(1, 0), a3, voffA);
;             PG8_WAIT_V(8); PG8_WAIT_L(0); PG8_BAR; PG8_MMA(1, 0, At, B0); PG8_MMA(1, 1, At, B1); PG8_BAR; PG8_SCHED;
	s_add_i32 s4, s42, s50
	v_lshl_add_u64 v[160:161], v[160:161], 0, s[22:23]
	s_mov_b32 m0, s4
	ds_read_b128 v[180:183], v225 offset:49152
	ds_read_b128 v[184:187], v225 offset:50176
	ds_read_b128 v[188:191], v225 offset:51200
	ds_read_b128 v[192:195], v225 offset:52224
	ds_read_b128 v[196:199], v225 offset:53248
	ds_read_b128 v[200:203], v225 offset:54272
	ds_read_b128 v[204:207], v225 offset:55296
	ds_read_b128 v[208:211], v225 offset:56320
	global_load_lds_dwordx4 v[160:161], off
	s_add_i32 m0, s4, 0x2000
	s_add_u32 s4, s6, 0xb0080
	v_lshl_add_u64 v[160:161], v[162:163], 0, s[22:23]
	s_addc_u32 s5, s7, 0
	s_add_i32 s6, s43, s50
	global_load_lds_dwordx4 v[160:161], off
	v_lshl_add_u64 v[160:161], s[4:5], 0, v[148:149]
	s_mov_b32 m0, s6
	s_nop 0
	global_load_lds_dwordx4 v[160:161], off
	v_lshl_add_u64 v[160:161], s[4:5], 0, v[152:153]
	s_add_i32 m0, s6, 0x2000
	s_nop 0
	global_load_lds_dwordx4 v[160:161], off
	v_lshl_add_u64 v[160:161], v[212:213], 0, s[24:25]
	s_mov_b32 m0, s63
	s_nop 0
	global_load_lds_dwordx4 v[160:161], off
	v_lshl_add_u64 v[160:161], v[214:215], 0, s[24:25]
	s_mov_b32 m0, s64
	s_nop 0
	global_load_lds_dwordx4 v[160:161], off
	s_waitcnt vmcnt(8)
	s_waitcnt lgkmcnt(0)
	s_barrier
	s_setprio 1
	s_waitcnt lgkmcnt(0)
	v_mfma_f32_16x16x32_bf16 v[62:65], v[130:133], v[180:183], v[62:65]
	v_mfma_f32_16x16x32_bf16 v[58:61], v[138:141], v[180:183], v[58:61]
	v_mfma_f32_16x16x32_bf16 v[46:49], v[130:133], v[188:191], v[46:49]
	v_mfma_f32_16x16x32_bf16 v[42:45], v[138:141], v[188:191], v[42:45]
	v_mfma_f32_16x16x32_bf16 v[30:33], v[130:133], v[196:199], v[30:33]
	v_mfma_f32_16x16x32_bf16 v[26:29], v[138:141], v[196:199], v[26:29]
	v_mfma_f32_16x16x32_bf16 v[14:17], v[130:133], v[204:207], v[14:17]
	v_mfma_f32_16x16x32_bf16 v[10:13], v[138:141], v[204:207], v[10:13]
	v_mfma_f32_16x16x32_bf16 v[62:65], v[134:137], v[184:187], v[62:65]
	v_mfma_f32_16x16x32_bf16 v[58:61], v[142:145], v[184:187], v[58:61]
	v_mfma_f32_16x16x32_bf16 v[46:49], v[134:137], v[192:195], v[46:49]
	v_mfma_f32_16x16x32_bf16 v[42:45], v[142:145], v[192:195], v[42:45]
	v_mfma_f32_16x16x32_bf16 v[30:33], v[134:137], v[200:203], v[30:33]
	v_mfma_f32_16x16x32_bf16 v[26:29], v[142:145], v[200:203], v[26:29]
	v_mfma_f32_16x16x32_bf16 v[14:17], v[134:137], v[208:211], v[14:17]
	v_mfma_f32_16x16x32_bf16 v[10:13], v[142:145], v[208:211], v[10:13]
	s_setprio 0
	s_setprio 1
	v_mfma_f32_16x16x32_bf16 v[54:57], v[164:167], v[180:183], v[54:57]
	v_mfma_f32_16x16x32_bf16 v[50:53], v[172:175], v[180:183], v[50:53]
	v_mfma_f32_16x16x32_bf16 v[38:41], v[164:167], v[188:191], v[38:41]
	v_mfma_f32_16x16x32_bf16 v[34:37], v[172:175], v[188:191], v[34:37]
	v_mfma_f32_16x16x32_bf16 v[22:25], v[164:167], v[196:199], v[22:25]
	v_mfma_f32_16x16x32_bf16 v[18:21], v[172:175], v[196:199], v[18:21]
	v_mfma_f32_16x16x32_bf16 v[6:9], v[164:167], v[204:207], v[6:9]
	v_mfma_f32_16x16x32_bf16 v[2:5], v[172:175], v[204:207], v[2:5]
	v_mfma_f32_16x16x32_bf16 v[54:57], v[168:171], v[184:187], v[54:57]
	v_mfma_f32_16x16x32_bf16 v[50:53], v[176:179], v[184:187], v[50:53]
	v_mfma_f32_16x16x32_bf16 v[38:41], v[168:171], v[192:195], v[38:41]
	v_mfma_f32_16x16x32_bf16 v[34:37], v[176:179], v[192:195], v[34:37]
	v_mfma_f32_16x16x32_bf16 v[22:25], v[168:171], v[200:203], v[22:25]
	v_mfma_f32_16x16x32_bf16 v[18:21], v[176:179], v[200:203], v[18:21]
	v_mfma_f32_16x16x32_bf16 v[6:9], v[168:171], v[208:211], v[6:9]
	v_mfma_f32_16x16x32_bf16 v[2:5], v[176:179], v[208:211], v[2:5]
	s_setprio 0
	s_add_i32 s41, s41, 2
	s_add_u32 s39, s39, 0x100
	s_addc_u32 s40, s40, 0
	s_cmp_gt_u32 s41, 41
	s_mov_b64 s[4:5], s[0:1]
	s_cbranch_scc0 .Lrb2
	s_barrier
	s_and_b64 vcc, exec, s[26:27]
	s_cbranch_vccz .LBB0_292
	s_barrier

; #define PG8_STAGE(bufoff, gbase, voff) do { _Pragma("unroll") for (int _i = 0; _i < 2; ++_i) \
;         __builtin_amdgcn_global_load_lds((const unsigned*)((const char*)(gbase) + (voff)[_i]), (PG8_LAS unsigned*)(lds + (bufoff) + ldsw + _i * 8192), 16, 0, 0); } while (0)
; #define PG8_LDA(dst, b, h) do { _Pragma("unroll") for (int m = 0; m < 4; ++m) _Pragma("unroll") for (int k = 0; k < 2; ++k) dst[m][k] = *(const PG8_LAS bf16x8*)(lds + PG8_SA(b, h) + aoff + m * 2048 + k * 1024); } while (0)
; #define PG8_LDB(dst, b, h) do { _Pragma("unroll") for (int n = 0; n < 2; ++n) _Pragma("unroll") for (int k = 0; k < 2; ++k) dst[n][k] = *(const PG8_LAS bf16x8*)(lds + PG8_SB(b, h) + boff + n * 2048 + k * 1024); } while (0)
; #define PG8_MMA(ai, bj, At, Bt) do { __builtin_amdgcn_s_setprio(1); _Pragma("unroll") for (int m = 0; m < 4; ++m) _Pragma("unroll") for (int n = 0; n < 2; ++n) _Pragma("unroll") for (int k = 0; k < 2; ++k) \
;         acc[ai][bj][m][n] = __builtin_amdgcn_mfma_f32_16x16x32_bf16(Bt[n][k], At[m][k], acc[ai][bj][m][n], 0, 0, 0); __builtin_amdgcn_s_setprio(0); } while (0)
; #define PG8_WAIT_V(n) asm volatile("s_waitcnt vmcnt(" #n ")" ::: "memory")
; #define PG8_WAIT_L(n) asm volatile("s_waitcnt lgkmcnt(" #n ")" ::: "memory")
; #define PG8_BAR __builtin_amdgcn_s_barrier()
; #define PG8_SCHED __builtin_amdgcn_sched_barrier(0)
; template <class Epi, class Sched, bool ALIGN_EPI = false, bool SP2 = false>
; __device__ __forceinline__ void gemm_phase(PG8_LAS unsigned char* lds, const Gemm g, const Sched& S, const Epi& E) {
;     ...
;             PG8_LDB(B0, 1, 0); PG8_LDB(B1, 1, 1); PG8_SCHED; PG8_LDA(At, 1, 0); PG8_STAGE(PG8_SA(0, 1), a2 + hstep, voffA);
;             PG8_WAIT_V(8); PG8_WAIT_L(0); PG8_BAR; PG8_MMA(0, 0, At, B0); PG8_MMA(0, 1, At, B1); PG8_BAR; PG8_SCHED;
.Lpz3_mid:
	s_add_i32 s29, 0, 0x18000
	v_add_u32_e32 v122, s29, v203
	s_add_i32 vcc_lo, 0, 0x1c000
	ds_read_b128 v[146:149], v122
	ds_read_b128 v[150:153], v122 offset:1024
	ds_read_b128 v[154:157], v122 offset:2048
	ds_read_b128 v[158:161], v122 offset:3072
	v_add_u32_e32 v122, vcc_lo, v203
	ds_read_b128 v[162:165], v122
	ds_read_b128 v[166:169], v122 offset:1024
	ds_read_b128 v[170:173], v122 offset:2048
	ds_read_b128 v[174:177], v122 offset:3072
	s_add_u32 s60, s60, 0x40000
	s_addc_u32 s61, s61, 0
	s_mov_b32 m0, s75
	v_lshl_add_u64 v[122:123], s[60:61], 0, v[178:179]
	ds_read_b128 v[212:215], v210 offset:32768
	ds_read_b128 v[216:219], v210 offset:33792
	ds_read_b128 v[222:225], v210 offset:34816
	ds_read_b128 v[226:229], v210 offset:35840
	ds_read_b128 v[230:233], v210 offset:36864
	ds_read_b128 v[234:237], v210 offset:37888
	ds_read_b128 v[238:241], v210 offset:38912
	ds_read_b128 v[242:245], v210 offset:39936
	global_load_lds_dwordx4 v[122:123], off
	v_lshl_add_u64 v[122:123], s[60:61], 0, v[182:183]
	s_mov_b32 m0, s76
	s_nop 0
	global_load_lds_dwordx4 v[122:123], off
	s_waitcnt vmcnt(8)
	s_waitcnt lgkmcnt(0)
	s_barrier
	s_setprio 1
	s_waitcnt lgkmcnt(0)
	v_mfma_f32_16x16x32_bf16 v[42:45], v[146:149], v[212:215], v[42:45]
	v_mfma_f32_16x16x32_bf16 v[142:145], v[150:153], v[216:219], v[42:45]
	v_mfma_f32_16x16x32_bf16 v[42:45], v[154:157], v[212:215], v[46:49]
	v_mfma_f32_16x16x32_bf16 v[138:141], v[158:161], v[216:219], v[42:45]
	v_mfma_f32_16x16x32_bf16 v[42:45], v[146:149], v[222:225], v[50:53]
	v_mfma_f32_16x16x32_bf16 v[126:129], v[150:153], v[226:229], v[42:45]
	v_mfma_f32_16x16x32_bf16 v[42:45], v[154:157], v[222:225], v[54:57]
	v_mfma_f32_16x16x32_bf16 v[122:125], v[158:161], v[226:229], v[42:45]
	v_mfma_f32_16x16x32_bf16 v[42:45], v[146:149], v[230:233], v[110:113]
	v_mfma_f32_16x16x32_bf16 v[110:113], v[150:153], v[234:237], v[42:45]
	v_mfma_f32_16x16x32_bf16 v[42:45], v[154:157], v[230:233], v[106:109]
	v_mfma_f32_16x16x32_bf16 v[106:109], v[158:161], v[234:237], v[42:45]
	v_mfma_f32_16x16x32_bf16 v[42:45], v[146:149], v[238:241], v[94:97]
	v_mfma_f32_16x16x32_bf16 v[94:97], v[150:153], v[242:245], v[42:45]
	v_mfma_f32_16x16x32_bf16 v[42:45], v[154:157], v[238:241], v[90:93]
	v_mfma_f32_16x16x32_bf16 v[90:93], v[158:161], v[242:245], v[42:45]
	s_setprio 0
	s_setprio 1
	v_mfma_f32_16x16x32_bf16 v[42:45], v[162:165], v[212:215], v[134:137]
	v_mfma_f32_16x16x32_bf16 v[134:137], v[166:169], v[216:219], v[42:45]
	v_mfma_f32_16x16x32_bf16 v[42:45], v[170:173], v[212:215], v[130:133]
	v_mfma_f32_16x16x32_bf16 v[130:133], v[174:177], v[216:219], v[42:45]
	v_mfma_f32_16x16x32_bf16 v[42:45], v[162:165], v[222:225], v[118:121]
	v_mfma_f32_16x16x32_bf16 v[118:121], v[166:169], v[226:229], v[42:45]
	v_mfma_f32_16x16x32_bf16 v[42:45], v[170:173], v[222:225], v[114:117]
	v_mfma_f32_16x16x32_bf16 v[114:117], v[174:177], v[226:229], v[42:45]
	v_mfma_f32_16x16x32_bf16 v[42:45], v[162:165], v[230:233], v[102:105]
	v_mfma_f32_16x16x32_bf16 v[102:105], v[166:169], v[234:237], v[42:45]
	v_mfma_f32_16x16x32_bf16 v[42:45], v[170:173], v[230:233], v[98:101]
	v_mfma_f32_16x16x32_bf16 v[98:101], v[174:177], v[234:237], v[42:45]
	v_mfma_f32_16x16x32_bf16 v[42:45], v[162:165], v[238:241], v[86:89]
	v_mfma_f32_16x16x32_bf16 v[86:89], v[166:169], v[242:245], v[42:45]
	v_mfma_f32_16x16x32_bf16 v[42:45], v[170:173], v[238:241], v[82:85]
	v_mfma_f32_16x16x32_bf16 v[82:85], v[174:177], v[242:245], v[42:45]
	s_setprio 0
	s_barrier
; #define PG8_STAGE(bufoff, gbase, voff) do { _Pragma("unroll") for (int _i = 0; _i < 2; ++_i) \
;         __builtin_amdgcn_global_load_lds((const unsigned*)((const char*)(gbase) + (voff)[_i]), (PG8_LAS unsigned*)(lds + (bufoff) + ldsw + _i * 8192), 16, 0, 0); } while (0)
; #define PG8_LDA(dst, b, h) do { _Pragma("unroll") for (int m = 0; m < 4; ++m) _Pragma("unroll") for (int k = 0; k < 2; ++k) dst[m][k] = *(const PG8_LAS bf16x8*)(lds + PG8_SA(b, h) + aoff + m * 2048 + k * 1024); } while (0)
; #define PG8_MMA(ai, bj, At, Bt) do { __builtin_amdgcn_s_setprio(1); _Pragma("unroll") for (int m = 0; m < 4; ++m) _Pragma("unroll") for (int n = 0; n < 2; ++n) _Pragma("unroll") for (int k = 0; k < 2; ++k) \
;         acc[ai][bj][m][n] = __builtin_amdgcn_mfma_f32_16x16x32_bf16(Bt[n][k], At[m][k], acc[ai][bj][m][n], 0, 0, 0); __builtin_amdgcn_s_setprio(0); } while (0)
; #define PG8_WAIT_V(n) asm volatile("s_waitcnt vmcnt(" #n ")" ::: "memory")
; #define PG8_WAIT_L(n) asm volatile("s_waitcnt lgkmcnt(" #n ")" ::: "memory")
; #define PG8_BAR __builtin_amdgcn_s_barrier()
; #define PG8_SCHED __builtin_amdgcn_sched_barrier(0)
; template <class Epi, class Sched, bool ALIGN_EPI = false, bool SP2 = false>
; __device__ __forceinline__ void gemm_phase(PG8_LAS unsigned char* lds, const Gemm g, const Sched& S, const Epi& E) {
;     ...
;         for (int t = 0; t < nt; t += 2) {
;             const bool last = (t == nt - 2);
;             const char* a1 = cA + (size_t)(t + 1) * kstepA;
;             const char* a2 = last ? nA : cA + (size_t)(t + 2) * kstepA; const char* b2 = last ? nB : cB + (size_t)(t + 2) * kstep;
;     ...
;             PG8_LDA(At, 1, 1); PG8_STAGE(PG8_SB(1, 0), b3, voffB); PG8_STAGE(PG8_SB(1, 1), b3 + hstep, voffB); PG8_STAGE(PG8_SA(1, 0), a3, voffA);
;             PG8_WAIT_V(8); PG8_WAIT_L(0); PG8_BAR; PG8_MMA(1, 0, At, B0); PG8_MMA(1, 1, At, B1); PG8_BAR; PG8_SCHED;
	s_add_i32 s29, s29, s68
	v_lshl_add_u64 v[204:205], v[204:205], 0, s[38:39]
	s_mov_b32 m0, s29
	s_nop 1
	ds_read_b128 v[42:45], v210 offset:49152
	ds_read_b128 v[46:49], v210 offset:50176
	ds_read_b128 v[50:53], v210 offset:51200
	ds_read_b128 v[54:57], v210 offset:52224
	ds_read_b128 v[212:215], v210 offset:53248
	ds_read_b128 v[216:219], v210 offset:54272
	ds_read_b128 v[222:225], v210 offset:55296
	ds_read_b128 v[226:229], v210 offset:56320
	global_load_lds_dwordx4 v[204:205], off
	s_add_i32 m0, s29, 0x2000
	s_add_u32 s58, s58, 0x40080
	v_lshl_add_u64 v[204:205], v[246:247], 0, s[38:39]
	s_addc_u32 s59, s59, 0
	s_add_i32 s29, vcc_lo, s68
	global_load_lds_dwordx4 v[204:205], off
	v_lshl_add_u64 v[204:205], s[58:59], 0, v[180:181]
	s_mov_b32 m0, s29
	s_nop 0
	global_load_lds_dwordx4 v[204:205], off
	v_lshl_add_u64 v[204:205], s[58:59], 0, v[184:185]
	s_add_i32 m0, s29, 0x2000
	s_nop 0
	global_load_lds_dwordx4 v[204:205], off
	v_lshl_add_u64 v[204:205], v[248:249], 0, s[38:39]
	s_mov_b32 m0, s81
	s_nop 0
	global_load_lds_dwordx4 v[204:205], off
	v_lshl_add_u64 v[204:205], v[250:251], 0, s[38:39]
	s_mov_b32 m0, s82
	s_nop 0
	global_load_lds_dwordx4 v[204:205], off
	s_waitcnt vmcnt(8)
	s_waitcnt lgkmcnt(0)
	s_barrier
	s_setprio 1
	s_waitcnt lgkmcnt(0)
	v_mfma_f32_16x16x32_bf16 v[78:81], v[146:149], v[42:45], v[78:81]
	v_mfma_f32_16x16x32_bf16 v[74:77], v[154:157], v[42:45], v[74:77]
	v_mfma_f32_16x16x32_bf16 v[62:65], v[146:149], v[50:53], v[62:65]
	v_mfma_f32_16x16x32_bf16 v[58:61], v[154:157], v[50:53], v[58:61]
	v_mfma_f32_16x16x32_bf16 v[30:33], v[146:149], v[212:215], v[30:33]
	v_mfma_f32_16x16x32_bf16 v[26:29], v[154:157], v[212:215], v[26:29]
	v_mfma_f32_16x16x32_bf16 v[14:17], v[146:149], v[222:225], v[14:17]
	v_mfma_f32_16x16x32_bf16 v[10:13], v[154:157], v[222:225], v[10:13]
	v_mfma_f32_16x16x32_bf16 v[78:81], v[150:153], v[46:49], v[78:81]
	v_mfma_f32_16x16x32_bf16 v[74:77], v[158:161], v[46:49], v[74:77]
	v_mfma_f32_16x16x32_bf16 v[62:65], v[150:153], v[54:57], v[62:65]
	v_mfma_f32_16x16x32_bf16 v[58:61], v[158:161], v[54:57], v[58:61]
	v_mfma_f32_16x16x32_bf16 v[30:33], v[150:153], v[216:219], v[30:33]
	v_mfma_f32_16x16x32_bf16 v[26:29], v[158:161], v[216:219], v[26:29]
	v_mfma_f32_16x16x32_bf16 v[14:17], v[150:153], v[226:229], v[14:17]
	v_mfma_f32_16x16x32_bf16 v[10:13], v[158:161], v[226:229], v[10:13]
	s_setprio 0
	s_setprio 1
	v_mfma_f32_16x16x32_bf16 v[70:73], v[162:165], v[42:45], v[70:73]
	v_mfma_f32_16x16x32_bf16 v[42:45], v[170:173], v[42:45], v[66:69]
	v_mfma_f32_16x16x32_bf16 v[38:41], v[162:165], v[50:53], v[38:41]
	v_mfma_f32_16x16x32_bf16 v[34:37], v[170:173], v[50:53], v[34:37]
	v_mfma_f32_16x16x32_bf16 v[22:25], v[162:165], v[212:215], v[22:25]
	v_mfma_f32_16x16x32_bf16 v[18:21], v[170:173], v[212:215], v[18:21]
	v_mfma_f32_16x16x32_bf16 v[6:9], v[162:165], v[222:225], v[6:9]
	v_mfma_f32_16x16x32_bf16 v[2:5], v[170:173], v[222:225], v[2:5]
	v_mfma_f32_16x16x32_bf16 v[70:73], v[166:169], v[46:49], v[70:73]
	v_mfma_f32_16x16x32_bf16 v[66:69], v[174:177], v[46:49], v[42:45]
	v_mfma_f32_16x16x32_bf16 v[38:41], v[166:169], v[54:57], v[38:41]
	v_mfma_f32_16x16x32_bf16 v[34:37], v[174:177], v[54:57], v[34:37]
	v_mfma_f32_16x16x32_bf16 v[22:25], v[166:169], v[216:219], v[22:25]
	v_mfma_f32_16x16x32_bf16 v[18:21], v[174:177], v[216:219], v[18:21]
	v_mfma_f32_16x16x32_bf16 v[6:9], v[166:169], v[226:229], v[6:9]
	v_mfma_f32_16x16x32_bf16 v[2:5], v[174:177], v[226:229], v[2:5]
	s_setprio 0
	s_add_i32 s29, s28, 2
	s_add_u32 s56, s56, 0x100
	s_addc_u32 s57, s57, 0
	s_cmp_gt_u32 s28, 13
	s_mov_b32 s28, s29
	s_cbranch_scc1 .Lrx1
	s_barrier

;     __host__ __device__ bool next(int i, Unit& u) const { if (!b.next(i >> 1, u)) return false; u.sel = i & 1; return true; }
; template <class Epi, class Sched, bool ALIGN_EPI = false, bool SP2 = false>
; __device__ __forceinline__ void gemm_phase(PG8_LAS unsigned char* lds, const Gemm g, const Sched& S, const Epi& E) {
;     ...
;         const bool has_next = S.next(ui + 1, nxt);
;         const char* nA = has_next ? PG8_ABASE(nxt) : cA; const char* nB = has_next ? PG8_BBASE(nxt) : cB;
;         for (int t = 0; t < nt; t += 2) {
;             const bool last = (t == nt - 2);
;             const char* a1 = cA + (size_t)(t + 1) * kstepA;
;             const char* a2 = last ? nA : cA + (size_t)(t + 2) * kstepA; const char* b2 = last ? nB : cB + (size_t)(t + 2) * kstep;
.LBB0_722:
	s_ashr_i32 s23, s22, 31
	s_lshl_b64 s[24:25], s[22:23], 19
	s_cmp_eq_u32 s70, 0
	s_cselect_b32 s23, s44, s51
	s_cselect_b32 s21, s45, s52
	s_cselect_b32 s36, s46, s53
	s_cselect_b32 s37, s47, s54
	s_add_u32 s24, s23, s24
	s_addc_u32 s25, s21, s25
	s_and_b64 s[26:27], s[2:3], exec
	s_cselect_b32 s23, s25, s1
	s_cselect_b32 s39, s24, s0
	s_ashr_i32 s21, s20, 31
	s_lshl_b64 s[26:27], s[20:21], 19
	s_add_u32 s26, s36, s26
	s_addc_u32 s27, s37, s27
	s_and_b64 s[36:37], s[2:3], exec
	s_cselect_b32 s21, s27, s29
	s_cselect_b32 s40, s26, s28
	s_add_u32 s0, s0, 0x40080
	s_addc_u32 s1, s1, 0
	s_add_u32 s41, s28, 0x100
	s_addc_u32 s42, s29, 0
	s_mov_b32 s43, -2
	s_branch .LBB0_723

; #define PG8_STAGE(bufoff, gbase, voff) do { _Pragma("unroll") for (int _i = 0; _i < 2; ++_i) \
;         __builtin_amdgcn_global_load_lds((const unsigned*)((const char*)(gbase) + (voff)[_i]), (PG8_LAS unsigned*)(lds + (bufoff) + ldsw + _i * 8192), 16, 0, 0); } while (0)
; #define PG8_LDA(dst, b, h) do { _Pragma("unroll") for (int m = 0; m < 4; ++m) _Pragma("unroll") for (int k = 0; k < 2; ++k) dst[m][k] = *(const PG8_LAS bf16x8*)(lds + PG8_SA(b, h) + aoff + m * 2048 + k * 1024); } while (0)
; #define PG8_LDB(dst, b, h) do { _Pragma("unroll") for (int n = 0; n < 2; ++n) _Pragma("unroll") for (int k = 0; k < 2; ++k) dst[n][k] = *(const PG8_LAS bf16x8*)(lds + PG8_SB(b, h) + boff + n * 2048 + k * 1024); } while (0)
; #define PG8_MMA(ai, bj, At, Bt) do { __builtin_amdgcn_s_setprio(1); _Pragma("unroll") for (int m = 0; m < 4; ++m) _Pragma("unroll") for (int n = 0; n < 2; ++n) _Pragma("unroll") for (int k = 0; k < 2; ++k) \
;         acc[ai][bj][m][n] = __builtin_amdgcn_mfma_f32_16x16x32_bf16(Bt[n][k], At[m][k], acc[ai][bj][m][n], 0, 0, 0); __builtin_amdgcn_s_setprio(0); } while (0)
; #define PG8_WAIT_V(n) asm volatile("s_waitcnt vmcnt(" #n ")" ::: "memory")
; template <class Epi, class Sched, bool ALIGN_EPI = false, bool SP2 = false>
; __device__ __forceinline__ void gemm_phase(PG8_LAS unsigned char* lds, const Gemm g, const Sched& S, const Epi& E) {
;     ...
;             const bool last = (t == nt - 2);
;             const char* a1 = cA + (size_t)(t + 1) * kstepA;
;             const char* a2 = last ? nA : cA + (size_t)(t + 2) * kstepA; const char* b2 = last ? nB : cB + (size_t)(t + 2) * kstep;
;             const char* a3 = a2 + kstepA; const char* b3 = b2 + kstep;
;             if (last && has_next) S.a_ready(nxt);
;             if constexpr (SP2) {
;             PG8_LDB(B0, 0, 0); PG8_LDB(B1, 0, 1); PG8_SCHED; PG8_LDA(At, 0, 0); PG8_STAGE(PG8_SA(1, 1), a1 + hstep, voffA);
;             PG8_WAIT_V(8); PG8_WAIT_L(0); PG8_BAR; PG8_MMA(0, 0, At, B0); PG8_MMA(0, 1, At, B1); PG8_BAR; PG8_SCHED;
;             if constexpr (Epi::PREFETCH) { if (t == tpf) E.prefetch(cur, wid, lane); }
;             PG8_LDA(At, 0, 1); PG8_STAGE(PG8_SB(0, 0), b2, voffB); PG8_STAGE(PG8_SB(0, 1), b2 + hstep, voffB); PG8_STAGE(PG8_SA(0, 0), a2, voffA);
;             PG8_WAIT_V(8); PG8_WAIT_L(0); PG8_BAR; PG8_MMA(1, 0, At, B0); PG8_MMA(1, 1, At, B1); PG8_BAR; PG8_SCHED;
.LBB0_723:
	v_add_u32_e32 v2, s67, v177
	ds_read_b128 v[134:137], v2
	ds_read_b128 v[138:141], v2 offset:1024
	ds_read_b128 v[142:145], v2 offset:2048
	ds_read_b128 v[146:149], v2 offset:3072
	v_add_u32_e32 v2, s68, v177
	ds_read_b128 v[150:153], v2
	ds_read_b128 v[170:173], v2 offset:1024
	ds_read_b128 v[180:183], v2 offset:2048
	ds_read_b128 v[184:187], v2 offset:3072
	s_add_u32 s28, s0, 0xfffc0080
	s_addc_u32 s29, s1, -1
	s_cmp_eq_u32 s43, 12
	s_cselect_b32 s37, s23, s29
	s_cselect_b32 s36, s39, s28
	s_cselect_b32 s29, s21, s42
	s_cselect_b32 s28, s40, s41
	v_lshl_add_u64 v[4:5], s[0:1], 0, v[162:163]
	s_add_i32 m0, s31, 0xc000
	ds_read_b128 v[188:191], v178
	ds_read_b128 v[192:195], v178 offset:1024
	ds_read_b128 v[196:199], v178 offset:2048
	ds_read_b128 v[200:203], v178 offset:3072
	ds_read_b128 v[204:207], v178 offset:4096
	ds_read_b128 v[208:211], v178 offset:5120
	ds_read_b128 v[212:215], v178 offset:6144
	ds_read_b128 v[216:219], v178 offset:7168
	global_load_lds_dwordx4 v[4:5], off
	v_lshl_add_u64 v[4:5], s[0:1], 0, v[164:165]
	s_add_i32 m0, s31, 0xe000
	s_nop 0
	global_load_lds_dwordx4 v[4:5], off
	s_waitcnt vmcnt(8)
	s_waitcnt lgkmcnt(0)
	s_barrier
	s_setprio 1
	s_waitcnt lgkmcnt(0)
	v_mfma_f32_16x16x32_bf16 v[130:133], v[134:137], v[188:191], v[130:133]
	v_mfma_f32_16x16x32_bf16 v[126:129], v[142:145], v[188:191], v[126:129]
	v_mfma_f32_16x16x32_bf16 v[122:125], v[134:137], v[196:199], v[122:125]
	v_mfma_f32_16x16x32_bf16 v[118:121], v[142:145], v[196:199], v[118:121]
	v_mfma_f32_16x16x32_bf16 v[114:117], v[134:137], v[204:207], v[114:117]
	v_mfma_f32_16x16x32_bf16 v[110:113], v[142:145], v[204:207], v[110:113]
	v_mfma_f32_16x16x32_bf16 v[106:109], v[134:137], v[212:215], v[106:109]
	v_mfma_f32_16x16x32_bf16 v[102:105], v[142:145], v[212:215], v[102:105]
	v_mfma_f32_16x16x32_bf16 v[130:133], v[138:141], v[192:195], v[130:133]
	v_mfma_f32_16x16x32_bf16 v[126:129], v[146:149], v[192:195], v[126:129]
	v_mfma_f32_16x16x32_bf16 v[122:125], v[138:141], v[200:203], v[122:125]
	v_mfma_f32_16x16x32_bf16 v[118:121], v[146:149], v[200:203], v[118:121]
	v_mfma_f32_16x16x32_bf16 v[114:117], v[138:141], v[208:211], v[114:117]
	v_mfma_f32_16x16x32_bf16 v[110:113], v[146:149], v[208:211], v[110:113]
	v_mfma_f32_16x16x32_bf16 v[106:109], v[138:141], v[216:219], v[106:109]
	v_mfma_f32_16x16x32_bf16 v[102:105], v[146:149], v[216:219], v[102:105]
	s_setprio 0
	s_setprio 1
	v_mfma_f32_16x16x32_bf16 v[98:101], v[150:153], v[188:191], v[98:101]
	v_mfma_f32_16x16x32_bf16 v[94:97], v[180:183], v[188:191], v[94:97]
	v_mfma_f32_16x16x32_bf16 v[90:93], v[150:153], v[196:199], v[90:93]
	v_mfma_f32_16x16x32_bf16 v[86:89], v[180:183], v[196:199], v[86:89]
	v_mfma_f32_16x16x32_bf16 v[82:85], v[150:153], v[204:207], v[82:85]
	v_mfma_f32_16x16x32_bf16 v[78:81], v[180:183], v[204:207], v[78:81]
	v_mfma_f32_16x16x32_bf16 v[74:77], v[150:153], v[212:215], v[74:77]
	v_mfma_f32_16x16x32_bf16 v[70:73], v[180:183], v[212:215], v[70:73]
	v_mfma_f32_16x16x32_bf16 v[98:101], v[170:173], v[192:195], v[98:101]
	v_mfma_f32_16x16x32_bf16 v[94:97], v[184:187], v[192:195], v[94:97]
	v_mfma_f32_16x16x32_bf16 v[90:93], v[170:173], v[200:203], v[90:93]
	v_mfma_f32_16x16x32_bf16 v[86:89], v[184:187], v[200:203], v[86:89]
	v_mfma_f32_16x16x32_bf16 v[82:85], v[170:173], v[208:211], v[82:85]
	v_mfma_f32_16x16x32_bf16 v[78:81], v[184:187], v[208:211], v[78:81]
	v_mfma_f32_16x16x32_bf16 v[74:77], v[170:173], v[216:219], v[74:77]
	v_mfma_f32_16x16x32_bf16 v[70:73], v[184:187], v[216:219], v[70:73]
	s_setprio 0
	s_barrier
	s_add_i32 s71, s67, s48
	v_lshl_add_u64 v[174:175], s[28:29], 0, v[156:157]
	s_mov_b32 m0, s71
	ds_read_b128 v[188:191], v178 offset:16384
	ds_read_b128 v[192:195], v178 offset:17408
	ds_read_b128 v[196:199], v178 offset:18432
	ds_read_b128 v[200:203], v178 offset:19456
	ds_read_b128 v[204:207], v178 offset:20480
	ds_read_b128 v[208:211], v178 offset:21504
	ds_read_b128 v[212:215], v178 offset:22528
	ds_read_b128 v[216:219], v178 offset:23552
	global_load_lds_dwordx4 v[174:175], off
	s_add_i32 m0, s71, 0x2000
	s_add_u32 s72, s28, 0x40000
	v_lshl_add_u64 v[222:223], s[28:29], 0, v[160:161]
	s_addc_u32 s73, s29, 0
	s_add_i32 s71, s68, s48
	global_load_lds_dwordx4 v[222:223], off
	v_lshl_add_u64 v[4:5], s[72:73], 0, v[156:157]
	s_mov_b32 m0, s71
	v_lshl_add_u64 v[224:225], s[36:37], 0, v[154:155]
	global_load_lds_dwordx4 v[4:5], off
	v_lshl_add_u64 v[4:5], s[72:73], 0, v[160:161]
	s_add_i32 m0, s71, 0x2000
	v_lshl_add_u64 v[226:227], s[36:37], 0, v[158:159]
	global_load_lds_dwordx4 v[4:5], off
	s_mov_b32 m0, s31
	s_nop 0
	global_load_lds_dwordx4 v[224:225], off
	s_mov_b32 m0, s35
	s_nop 0
	global_load_lds_dwordx4 v[226:227], off
	s_waitcnt vmcnt(8)
	s_waitcnt lgkmcnt(0)
	s_barrier
; #define PG8_STAGE(bufoff, gbase, voff) do { _Pragma("unroll") for (int _i = 0; _i < 2; ++_i) \
;         __builtin_amdgcn_global_load_lds((const unsigned*)((const char*)(gbase) + (voff)[_i]), (PG8_LAS unsigned*)(lds + (bufoff) + ldsw + _i * 8192), 16, 0, 0); } while (0)
; #define PG8_LDA(dst, b, h) do { _Pragma("unroll") for (int m = 0; m < 4; ++m) _Pragma("unroll") for (int k = 0; k < 2; ++k) dst[m][k] = *(const PG8_LAS bf16x8*)(lds + PG8_SA(b, h) + aoff + m * 2048 + k * 1024); } while (0)
; #define PG8_LDB(dst, b, h) do { _Pragma("unroll") for (int n = 0; n < 2; ++n) _Pragma("unroll") for (int k = 0; k < 2; ++k) dst[n][k] = *(const PG8_LAS bf16x8*)(lds + PG8_SB(b, h) + boff + n * 2048 + k * 1024); } while (0)
; #define PG8_MMA(ai, bj, At, Bt) do { __builtin_amdgcn_s_setprio(1); _Pragma("unroll") for (int m = 0; m < 4; ++m) _Pragma("unroll") for (int n = 0; n < 2; ++n) _Pragma("unroll") for (int k = 0; k < 2; ++k) \
;         acc[ai][bj][m][n] = __builtin_amdgcn_mfma_f32_16x16x32_bf16(Bt[n][k], At[m][k], acc[ai][bj][m][n], 0, 0, 0); __builtin_amdgcn_s_setprio(0); } while (0)
; #define PG8_WAIT_V(n) asm volatile("s_waitcnt vmcnt(" #n ")" ::: "memory")
; #define PG8_WAIT_L(n) asm volatile("s_waitcnt lgkmcnt(" #n ")" ::: "memory")
; #define PG8_BAR __builtin_amdgcn_s_barrier()
; #define PG8_SCHED __builtin_amdgcn_sched_barrier(0)
; template <class Epi, class Sched, bool ALIGN_EPI = false, bool SP2 = false>
; __device__ __forceinline__ void gemm_phase(PG8_LAS unsigned char* lds, const Gemm g, const Sched& S, const Epi& E) {
;     ...
;             PG8_WAIT_V(8); PG8_WAIT_L(0); PG8_BAR; PG8_MMA(1, 0, At, B0); PG8_MMA(1, 1, At, B1); PG8_BAR; PG8_SCHED;
;             PG8_LDB(B0, 1, 0); PG8_LDB(B1, 1, 1); PG8_SCHED; PG8_LDA(At, 1, 0); PG8_STAGE(PG8_SA(0, 1), a2 + hstep, voffA);
;             PG8_WAIT_V(8); PG8_WAIT_L(0); PG8_BAR; PG8_MMA(0, 0, At, B0); PG8_MMA(0, 1, At, B1); PG8_BAR; PG8_SCHED;
	s_setprio 1
	s_waitcnt lgkmcnt(0)
	v_mfma_f32_16x16x32_bf16 v[66:69], v[134:137], v[188:191], v[66:69]
	v_mfma_f32_16x16x32_bf16 v[62:65], v[142:145], v[188:191], v[62:65]
	v_mfma_f32_16x16x32_bf16 v[58:61], v[134:137], v[196:199], v[58:61]
	v_mfma_f32_16x16x32_bf16 v[54:57], v[142:145], v[196:199], v[54:57]
	v_mfma_f32_16x16x32_bf16 v[50:53], v[134:137], v[204:207], v[50:53]
	v_mfma_f32_16x16x32_bf16 v[46:49], v[142:145], v[204:207], v[46:49]
	v_mfma_f32_16x16x32_bf16 v[42:45], v[134:137], v[212:215], v[42:45]
	v_mfma_f32_16x16x32_bf16 v[38:41], v[142:145], v[212:215], v[38:41]
	v_mfma_f32_16x16x32_bf16 v[66:69], v[138:141], v[192:195], v[66:69]
	v_mfma_f32_16x16x32_bf16 v[62:65], v[146:149], v[192:195], v[62:65]
	v_mfma_f32_16x16x32_bf16 v[58:61], v[138:141], v[200:203], v[58:61]
	v_mfma_f32_16x16x32_bf16 v[54:57], v[146:149], v[200:203], v[54:57]
	v_mfma_f32_16x16x32_bf16 v[50:53], v[138:141], v[208:211], v[50:53]
	v_mfma_f32_16x16x32_bf16 v[46:49], v[146:149], v[208:211], v[46:49]
	v_mfma_f32_16x16x32_bf16 v[42:45], v[138:141], v[216:219], v[42:45]
	v_mfma_f32_16x16x32_bf16 v[38:41], v[146:149], v[216:219], v[38:41]
	s_setprio 0
	s_setprio 1
	v_mfma_f32_16x16x32_bf16 v[34:37], v[150:153], v[188:191], v[34:37]
	v_mfma_f32_16x16x32_bf16 v[30:33], v[180:183], v[188:191], v[30:33]
	v_mfma_f32_16x16x32_bf16 v[26:29], v[150:153], v[196:199], v[26:29]
	v_mfma_f32_16x16x32_bf16 v[22:25], v[180:183], v[196:199], v[22:25]
	v_mfma_f32_16x16x32_bf16 v[18:21], v[150:153], v[204:207], v[18:21]
	v_mfma_f32_16x16x32_bf16 v[14:17], v[180:183], v[204:207], v[14:17]
	v_mfma_f32_16x16x32_bf16 v[10:13], v[150:153], v[212:215], v[10:13]
	v_mfma_f32_16x16x32_bf16 v[4:7], v[180:183], v[212:215], v[6:9]
	v_mfma_f32_16x16x32_bf16 v[34:37], v[170:173], v[192:195], v[34:37]
	v_mfma_f32_16x16x32_bf16 v[30:33], v[184:187], v[192:195], v[30:33]
	v_mfma_f32_16x16x32_bf16 v[26:29], v[170:173], v[200:203], v[26:29]
	v_mfma_f32_16x16x32_bf16 v[22:25], v[184:187], v[200:203], v[22:25]
	v_mfma_f32_16x16x32_bf16 v[18:21], v[170:173], v[208:211], v[18:21]
	v_mfma_f32_16x16x32_bf16 v[14:17], v[184:187], v[208:211], v[14:17]
	v_mfma_f32_16x16x32_bf16 v[10:13], v[170:173], v[216:219], v[10:13]
	v_mfma_f32_16x16x32_bf16 v[4:7], v[184:187], v[216:219], v[4:7]
	s_setprio 0
	s_barrier
	s_add_i32 s71, 0, 0x18000
	v_add_u32_e32 v2, s71, v177
	s_add_i32 s72, 0, 0x1c000
	ds_read_b128 v[134:137], v2
	ds_read_b128 v[138:141], v2 offset:1024
	ds_read_b128 v[142:145], v2 offset:2048
	ds_read_b128 v[146:149], v2 offset:3072
	v_add_u32_e32 v2, s72, v177
	ds_read_b128 v[150:153], v2
	ds_read_b128 v[170:173], v2 offset:1024
	ds_read_b128 v[180:183], v2 offset:2048
	ds_read_b128 v[184:187], v2 offset:3072
	s_add_u32 s36, s36, 0x40000
	s_addc_u32 s37, s37, 0
	s_mov_b32 m0, s49
	v_lshl_add_u64 v[8:9], s[36:37], 0, v[154:155]
	ds_read_b128 v[188:191], v178 offset:32768
	ds_read_b128 v[192:195], v178 offset:33792
	ds_read_b128 v[196:199], v178 offset:34816
	ds_read_b128 v[200:203], v178 offset:35840
	ds_read_b128 v[204:207], v178 offset:36864
	ds_read_b128 v[208:211], v178 offset:37888
	ds_read_b128 v[212:215], v178 offset:38912
	ds_read_b128 v[216:219], v178 offset:39936
	global_load_lds_dwordx4 v[8:9], off
	v_lshl_add_u64 v[8:9], s[36:37], 0, v[158:159]
	s_mov_b32 m0, s50
	s_nop 0
	global_load_lds_dwordx4 v[8:9], off
	s_waitcnt vmcnt(8)
	s_waitcnt lgkmcnt(0)
	s_barrier
	s_setprio 1
	s_waitcnt lgkmcnt(0)
	v_mfma_f32_16x16x32_bf16 v[130:133], v[134:137], v[188:191], v[130:133]
	v_mfma_f32_16x16x32_bf16 v[126:129], v[142:145], v[188:191], v[126:129]
	v_mfma_f32_16x16x32_bf16 v[122:125], v[134:137], v[196:199], v[122:125]
	v_mfma_f32_16x16x32_bf16 v[118:121], v[142:145], v[196:199], v[118:121]
	v_mfma_f32_16x16x32_bf16 v[114:117], v[134:137], v[204:207], v[114:117]
	v_mfma_f32_16x16x32_bf16 v[110:113], v[142:145], v[204:207], v[110:113]
	v_mfma_f32_16x16x32_bf16 v[106:109], v[134:137], v[212:215], v[106:109]
	v_mfma_f32_16x16x32_bf16 v[102:105], v[142:145], v[212:215], v[102:105]
	v_mfma_f32_16x16x32_bf16 v[130:133], v[138:141], v[192:195], v[130:133]
	v_mfma_f32_16x16x32_bf16 v[126:129], v[146:149], v[192:195], v[126:129]
	v_mfma_f32_16x16x32_bf16 v[122:125], v[138:141], v[200:203], v[122:125]
	v_mfma_f32_16x16x32_bf16 v[118:121], v[146:149], v[200:203], v[118:121]
	v_mfma_f32_16x16x32_bf16 v[114:117], v[138:141], v[208:211], v[114:117]
	v_mfma_f32_16x16x32_bf16 v[110:113], v[146:149], v[208:211], v[110:113]
	v_mfma_f32_16x16x32_bf16 v[106:109], v[138:141], v[216:219], v[106:109]
	v_mfma_f32_16x16x32_bf16 v[102:105], v[146:149], v[216:219], v[102:105]
	s_setprio 0
	s_setprio 1
	v_mfma_f32_16x16x32_bf16 v[98:101], v[150:153], v[188:191], v[98:101]
	v_mfma_f32_16x16x32_bf16 v[94:97], v[180:183], v[188:191], v[94:97]
	v_mfma_f32_16x16x32_bf16 v[90:93], v[150:153], v[196:199], v[90:93]
	v_mfma_f32_16x16x32_bf16 v[86:89], v[180:183], v[196:199], v[86:89]
	v_mfma_f32_16x16x32_bf16 v[82:85], v[150:153], v[204:207], v[82:85]
	v_mfma_f32_16x16x32_bf16 v[78:81], v[180:183], v[204:207], v[78:81]
	v_mfma_f32_16x16x32_bf16 v[74:77], v[150:153], v[212:215], v[74:77]
	v_mfma_f32_16x16x32_bf16 v[70:73], v[180:183], v[212:215], v[70:73]
	v_mfma_f32_16x16x32_bf16 v[98:101], v[170:173], v[192:195], v[98:101]
	v_mfma_f32_16x16x32_bf16 v[94:97], v[184:187], v[192:195], v[94:97]
	v_mfma_f32_16x16x32_bf16 v[90:93], v[170:173], v[200:203], v[90:93]
	v_mfma_f32_16x16x32_bf16 v[86:89], v[184:187], v[200:203], v[86:89]
	v_mfma_f32_16x16x32_bf16 v[82:85], v[170:173], v[208:211], v[82:85]
	v_mfma_f32_16x16x32_bf16 v[78:81], v[184:187], v[208:211], v[78:81]
	v_mfma_f32_16x16x32_bf16 v[74:77], v[170:173], v[216:219], v[74:77]
	v_mfma_f32_16x16x32_bf16 v[70:73], v[184:187], v[216:219], v[70:73]
	s_setprio 0
	s_barrier
; #define PG8_STAGE(bufoff, gbase, voff) do { _Pragma("unroll") for (int _i = 0; _i < 2; ++_i) \
;         __builtin_amdgcn_global_load_lds((const unsigned*)((const char*)(gbase) + (voff)[_i]), (PG8_LAS unsigned*)(lds + (bufoff) + ldsw + _i * 8192), 16, 0, 0); } while (0)
; #define PG8_LDA(dst, b, h) do { _Pragma("unroll") for (int m = 0; m < 4; ++m) _Pragma("unroll") for (int k = 0; k < 2; ++k) dst[m][k] = *(const PG8_LAS bf16x8*)(lds + PG8_SA(b, h) + aoff + m * 2048 + k * 1024); } while (0)
; #define PG8_MMA(ai, bj, At, Bt) do { __builtin_amdgcn_s_setprio(1); _Pragma("unroll") for (int m = 0; m < 4; ++m) _Pragma("unroll") for (int n = 0; n < 2; ++n) _Pragma("unroll") for (int k = 0; k < 2; ++k) \
;         acc[ai][bj][m][n] = __builtin_amdgcn_mfma_f32_16x16x32_bf16(Bt[n][k], At[m][k], acc[ai][bj][m][n], 0, 0, 0); __builtin_amdgcn_s_setprio(0); } while (0)
; #define PG8_WAIT_V(n) asm volatile("s_waitcnt vmcnt(" #n ")" ::: "memory")
; #define PG8_WAIT_L(n) asm volatile("s_waitcnt lgkmcnt(" #n ")" ::: "memory")
; #define PG8_BAR __builtin_amdgcn_s_barrier()
; #define PG8_SCHED __builtin_amdgcn_sched_barrier(0)
; template <class Epi, class Sched, bool ALIGN_EPI = false, bool SP2 = false>
; __device__ __forceinline__ void gemm_phase(PG8_LAS unsigned char* lds, const Gemm g, const Sched& S, const Epi& E) {
;     ...
;         for (int t = 0; t < nt; t += 2) {
;             const bool last = (t == nt - 2);
;     ...
;             PG8_LDA(At, 1, 1); PG8_STAGE(PG8_SB(1, 0), b3, voffB); PG8_STAGE(PG8_SB(1, 1), b3 + hstep, voffB); PG8_STAGE(PG8_SA(1, 0), a3, voffA);
;             PG8_WAIT_V(8); PG8_WAIT_L(0); PG8_BAR; PG8_MMA(1, 0, At, B0); PG8_MMA(1, 1, At, B1); PG8_BAR; PG8_SCHED;
	s_add_i32 s36, s71, s48
	v_lshl_add_u64 v[8:9], v[174:175], 0, s[14:15]
	s_mov_b32 m0, s36
	ds_read_b128 v[188:191], v178 offset:49152
	ds_read_b128 v[192:195], v178 offset:50176
	ds_read_b128 v[196:199], v178 offset:51200
	ds_read_b128 v[200:203], v178 offset:52224
	ds_read_b128 v[204:207], v178 offset:53248
	ds_read_b128 v[208:211], v178 offset:54272
	ds_read_b128 v[212:215], v178 offset:55296
	ds_read_b128 v[216:219], v178 offset:56320
	global_load_lds_dwordx4 v[8:9], off
	s_add_i32 m0, s36, 0x2000
	s_add_u32 s28, s28, 0x40080
	v_lshl_add_u64 v[8:9], v[222:223], 0, s[14:15]
	s_addc_u32 s29, s29, 0
	s_add_i32 s36, s72, s48
	global_load_lds_dwordx4 v[8:9], off
	v_lshl_add_u64 v[8:9], s[28:29], 0, v[156:157]
	s_mov_b32 m0, s36
	s_nop 0
	global_load_lds_dwordx4 v[8:9], off
	v_lshl_add_u64 v[8:9], s[28:29], 0, v[160:161]
	s_add_i32 m0, s36, 0x2000
	s_nop 0
	global_load_lds_dwordx4 v[8:9], off
	v_lshl_add_u64 v[8:9], v[224:225], 0, s[14:15]
	s_mov_b32 m0, s58
	s_nop 0
	global_load_lds_dwordx4 v[8:9], off
	v_lshl_add_u64 v[8:9], v[226:227], 0, s[14:15]
	s_mov_b32 m0, s59
	s_nop 0
	global_load_lds_dwordx4 v[8:9], off
	s_waitcnt vmcnt(8)
	s_waitcnt lgkmcnt(0)
	s_barrier
	s_setprio 1
	s_waitcnt lgkmcnt(0)
	v_mfma_f32_16x16x32_bf16 v[66:69], v[134:137], v[188:191], v[66:69]
	v_mfma_f32_16x16x32_bf16 v[62:65], v[142:145], v[188:191], v[62:65]
	v_mfma_f32_16x16x32_bf16 v[58:61], v[134:137], v[196:199], v[58:61]
	v_mfma_f32_16x16x32_bf16 v[54:57], v[142:145], v[196:199], v[54:57]
	v_mfma_f32_16x16x32_bf16 v[50:53], v[134:137], v[204:207], v[50:53]
	v_mfma_f32_16x16x32_bf16 v[46:49], v[142:145], v[204:207], v[46:49]
	v_mfma_f32_16x16x32_bf16 v[42:45], v[134:137], v[212:215], v[42:45]
	v_mfma_f32_16x16x32_bf16 v[38:41], v[142:145], v[212:215], v[38:41]
	v_mfma_f32_16x16x32_bf16 v[66:69], v[138:141], v[192:195], v[66:69]
	v_mfma_f32_16x16x32_bf16 v[62:65], v[146:149], v[192:195], v[62:65]
	v_mfma_f32_16x16x32_bf16 v[58:61], v[138:141], v[200:203], v[58:61]
	v_mfma_f32_16x16x32_bf16 v[54:57], v[146:149], v[200:203], v[54:57]
	v_mfma_f32_16x16x32_bf16 v[50:53], v[138:141], v[208:211], v[50:53]
	v_mfma_f32_16x16x32_bf16 v[46:49], v[146:149], v[208:211], v[46:49]
	v_mfma_f32_16x16x32_bf16 v[42:45], v[138:141], v[216:219], v[42:45]
	v_mfma_f32_16x16x32_bf16 v[38:41], v[146:149], v[216:219], v[38:41]
	s_setprio 0
	s_setprio 1
	v_mfma_f32_16x16x32_bf16 v[34:37], v[150:153], v[188:191], v[34:37]
	v_mfma_f32_16x16x32_bf16 v[30:33], v[180:183], v[188:191], v[30:33]
	v_mfma_f32_16x16x32_bf16 v[26:29], v[150:153], v[196:199], v[26:29]
	v_mfma_f32_16x16x32_bf16 v[22:25], v[180:183], v[196:199], v[22:25]
	v_mfma_f32_16x16x32_bf16 v[18:21], v[150:153], v[204:207], v[18:21]
	v_mfma_f32_16x16x32_bf16 v[14:17], v[180:183], v[204:207], v[14:17]
	v_mfma_f32_16x16x32_bf16 v[8:11], v[150:153], v[212:215], v[10:13]
	v_mfma_f32_16x16x32_bf16 v[4:7], v[180:183], v[212:215], v[4:7]
	v_mfma_f32_16x16x32_bf16 v[34:37], v[170:173], v[192:195], v[34:37]
	v_mfma_f32_16x16x32_bf16 v[30:33], v[184:187], v[192:195], v[30:33]
	v_mfma_f32_16x16x32_bf16 v[26:29], v[170:173], v[200:203], v[26:29]
	v_mfma_f32_16x16x32_bf16 v[22:25], v[184:187], v[200:203], v[22:25]
	v_mfma_f32_16x16x32_bf16 v[18:21], v[170:173], v[208:211], v[18:21]
	v_mfma_f32_16x16x32_bf16 v[14:17], v[184:187], v[208:211], v[14:17]
	v_mfma_f32_16x16x32_bf16 v[10:13], v[170:173], v[216:219], v[8:11]
	v_mfma_f32_16x16x32_bf16 v[6:9], v[184:187], v[216:219], v[4:7]
	s_setprio 0
	s_add_i32 s43, s43, 2
	s_add_u32 s0, s0, 0x100
	s_addc_u32 s1, s1, 0
	s_add_u32 s41, s41, 0x100
	s_addc_u32 s42, s42, 0
	s_cmp_gt_u32 s43, 13
	s_cbranch_scc0 .Lrb5
	s_barrier
	s_and_b64 vcc, exec, s[16:17]
	s_cbranch_vccz .LBB0_726
	s_barrier

; #define PG8_STAGE(bufoff, gbase, voff) do { _Pragma("unroll") for (int _i = 0; _i < 2; ++_i) \
;         __builtin_amdgcn_global_load_lds((const unsigned*)((const char*)(gbase) + (voff)[_i]), (PG8_LAS unsigned*)(lds + (bufoff) + ldsw + _i * 8192), 16, 0, 0); } while (0)
; #define PG8_LDA(dst, b, h) do { _Pragma("unroll") for (int m = 0; m < 4; ++m) _Pragma("unroll") for (int k = 0; k < 2; ++k) dst[m][k] = *(const PG8_LAS bf16x8*)(lds + PG8_SA(b, h) + aoff + m * 2048 + k * 1024); } while (0)
; #define PG8_LDB(dst, b, h) do { _Pragma("unroll") for (int n = 0; n < 2; ++n) _Pragma("unroll") for (int k = 0; k < 2; ++k) dst[n][k] = *(const PG8_LAS bf16x8*)(lds + PG8_SB(b, h) + boff + n * 2048 + k * 1024); } while (0)
; #define PG8_MMA(ai, bj, At, Bt) do { __builtin_amdgcn_s_setprio(1); _Pragma("unroll") for (int m = 0; m < 4; ++m) _Pragma("unroll") for (int n = 0; n < 2; ++n) _Pragma("unroll") for (int k = 0; k < 2; ++k) \
;         acc[ai][bj][m][n] = __builtin_amdgcn_mfma_f32_16x16x32_bf16(Bt[n][k], At[m][k], acc[ai][bj][m][n], 0, 0, 0); __builtin_amdgcn_s_setprio(0); } while (0)
; #define PG8_WAIT_V(n) asm volatile("s_waitcnt vmcnt(" #n ")" ::: "memory")
; #define PG8_WAIT_L(n) asm volatile("s_waitcnt lgkmcnt(" #n ")" ::: "memory")
; #define PG8_BAR __builtin_amdgcn_s_barrier()
; #define PG8_SCHED __builtin_amdgcn_sched_barrier(0)
; template <class Epi, class Sched, bool ALIGN_EPI = false, bool SP2 = false>
; __device__ __forceinline__ void gemm_phase(PG8_LAS unsigned char* lds, const Gemm g, const Sched& S, const Epi& E) {
;     ...
;             PG8_LDB(B0, 1, 0); PG8_LDB(B1, 1, 1); PG8_SCHED; PG8_LDA(At, 1, 0); PG8_STAGE(PG8_SA(0, 1), a2 + hstep, voffA);
;             PG8_WAIT_V(8); PG8_WAIT_L(0); PG8_BAR; PG8_MMA(0, 0, At, B0); PG8_MMA(0, 1, At, B1); PG8_BAR; PG8_SCHED;
.Lpz4_mid:
	s_add_i32 s42, 0, 0x18000
	s_add_i32 s43, 0, 0x1c000
	v_add_u32_e32 v70, s42, v213
	v_add_u32_e32 v162, s43, v213
	ds_read_b128 v[58:61], v70
	ds_read_b128 v[62:65], v70 offset:1024
	ds_read_b128 v[66:69], v70 offset:2048
	ds_read_b128 v[70:73], v70 offset:3072
	ds_read_b128 v[146:149], v162
	ds_read_b128 v[150:153], v162 offset:1024
	ds_read_b128 v[172:175], v162 offset:2048
	ds_read_b128 v[176:179], v162 offset:3072
	s_add_u32 s36, s36, 0x40000
	s_addc_u32 s37, s37, 0
	s_mov_b32 m0, s53
	v_lshl_add_u64 v[228:229], s[36:37], 0, v[154:155]
	ds_read_b128 v[180:183], v216 offset:32768
	ds_read_b128 v[184:187], v216 offset:33792
	ds_read_b128 v[188:191], v216 offset:34816
	ds_read_b128 v[192:195], v216 offset:35840
	ds_read_b128 v[196:199], v216 offset:36864
	ds_read_b128 v[200:203], v216 offset:37888
	ds_read_b128 v[204:207], v216 offset:38912
	ds_read_b128 v[208:211], v216 offset:39936
	global_load_lds_dwordx4 v[228:229], off
	v_lshl_add_u64 v[228:229], s[36:37], 0, v[158:159]
	s_mov_b32 m0, s54
	s_nop 0
	global_load_lds_dwordx4 v[228:229], off
	s_waitcnt vmcnt(8)
	s_waitcnt lgkmcnt(0)
	s_barrier
	s_setprio 1
	s_waitcnt lgkmcnt(0)
	v_mfma_f32_16x16x32_bf16 v[142:145], v[58:61], v[180:183], v[142:145]
	v_mfma_f32_16x16x32_bf16 v[138:141], v[66:69], v[180:183], v[138:141]
	v_mfma_f32_16x16x32_bf16 v[126:129], v[58:61], v[188:191], v[126:129]
	v_mfma_f32_16x16x32_bf16 v[122:125], v[66:69], v[188:191], v[122:125]
	v_mfma_f32_16x16x32_bf16 v[110:113], v[58:61], v[196:199], v[110:113]
	v_mfma_f32_16x16x32_bf16 v[106:109], v[66:69], v[196:199], v[106:109]
	v_mfma_f32_16x16x32_bf16 v[94:97], v[58:61], v[204:207], v[94:97]
	v_mfma_f32_16x16x32_bf16 v[90:93], v[66:69], v[204:207], v[90:93]
	v_mfma_f32_16x16x32_bf16 v[142:145], v[62:65], v[184:187], v[142:145]
	v_mfma_f32_16x16x32_bf16 v[138:141], v[70:73], v[184:187], v[138:141]
	v_mfma_f32_16x16x32_bf16 v[126:129], v[62:65], v[192:195], v[126:129]
	v_mfma_f32_16x16x32_bf16 v[122:125], v[70:73], v[192:195], v[122:125]
	v_mfma_f32_16x16x32_bf16 v[110:113], v[62:65], v[200:203], v[110:113]
	v_mfma_f32_16x16x32_bf16 v[106:109], v[70:73], v[200:203], v[106:109]
	v_mfma_f32_16x16x32_bf16 v[94:97], v[62:65], v[208:211], v[94:97]
	v_mfma_f32_16x16x32_bf16 v[90:93], v[70:73], v[208:211], v[90:93]
	s_setprio 0
	s_setprio 1
	v_mfma_f32_16x16x32_bf16 v[134:137], v[146:149], v[180:183], v[134:137]
	v_mfma_f32_16x16x32_bf16 v[130:133], v[172:175], v[180:183], v[130:133]
	v_mfma_f32_16x16x32_bf16 v[118:121], v[146:149], v[188:191], v[118:121]
	v_mfma_f32_16x16x32_bf16 v[114:117], v[172:175], v[188:191], v[114:117]
	v_mfma_f32_16x16x32_bf16 v[102:105], v[146:149], v[196:199], v[102:105]
	v_mfma_f32_16x16x32_bf16 v[98:101], v[172:175], v[196:199], v[98:101]
	v_mfma_f32_16x16x32_bf16 v[86:89], v[146:149], v[204:207], v[86:89]
	v_mfma_f32_16x16x32_bf16 v[82:85], v[172:175], v[204:207], v[82:85]
	v_mfma_f32_16x16x32_bf16 v[134:137], v[150:153], v[184:187], v[134:137]
	v_mfma_f32_16x16x32_bf16 v[130:133], v[176:179], v[184:187], v[130:133]
	v_mfma_f32_16x16x32_bf16 v[118:121], v[150:153], v[192:195], v[118:121]
	v_mfma_f32_16x16x32_bf16 v[114:117], v[176:179], v[192:195], v[114:117]
	v_mfma_f32_16x16x32_bf16 v[102:105], v[150:153], v[200:203], v[102:105]
	v_mfma_f32_16x16x32_bf16 v[98:101], v[176:179], v[200:203], v[98:101]
	v_mfma_f32_16x16x32_bf16 v[86:89], v[150:153], v[208:211], v[86:89]
	v_mfma_f32_16x16x32_bf16 v[82:85], v[176:179], v[208:211], v[82:85]
	s_setprio 0
	s_barrier
; #define PG8_STAGE(bufoff, gbase, voff) do { _Pragma("unroll") for (int _i = 0; _i < 2; ++_i) \
;         __builtin_amdgcn_global_load_lds((const unsigned*)((const char*)(gbase) + (voff)[_i]), (PG8_LAS unsigned*)(lds + (bufoff) + ldsw + _i * 8192), 16, 0, 0); } while (0)
; #define PG8_LDA(dst, b, h) do { _Pragma("unroll") for (int m = 0; m < 4; ++m) _Pragma("unroll") for (int k = 0; k < 2; ++k) dst[m][k] = *(const PG8_LAS bf16x8*)(lds + PG8_SA(b, h) + aoff + m * 2048 + k * 1024); } while (0)
; #define PG8_MMA(ai, bj, At, Bt) do { __builtin_amdgcn_s_setprio(1); _Pragma("unroll") for (int m = 0; m < 4; ++m) _Pragma("unroll") for (int n = 0; n < 2; ++n) _Pragma("unroll") for (int k = 0; k < 2; ++k) \
;         acc[ai][bj][m][n] = __builtin_amdgcn_mfma_f32_16x16x32_bf16(Bt[n][k], At[m][k], acc[ai][bj][m][n], 0, 0, 0); __builtin_amdgcn_s_setprio(0); } while (0)
; #define PG8_WAIT_V(n) asm volatile("s_waitcnt vmcnt(" #n ")" ::: "memory")
; #define PG8_WAIT_L(n) asm volatile("s_waitcnt lgkmcnt(" #n ")" ::: "memory")
; #define PG8_BAR __builtin_amdgcn_s_barrier()
; #define PG8_SCHED __builtin_amdgcn_sched_barrier(0)
; template <class Epi, class Sched, bool ALIGN_EPI = false, bool SP2 = false>
; __device__ __forceinline__ void gemm_phase(PG8_LAS unsigned char* lds, const Gemm g, const Sched& S, const Epi& E) {
;     ...
;         for (int t = 0; t < nt; t += 2) {
;             const bool last = (t == nt - 2);
;     ...
;             PG8_LDA(At, 1, 1); PG8_STAGE(PG8_SB(1, 0), b3, voffB); PG8_STAGE(PG8_SB(1, 1), b3 + hstep, voffB); PG8_STAGE(PG8_SA(1, 0), a3, voffA);
;             PG8_WAIT_V(8); PG8_WAIT_L(0); PG8_BAR; PG8_MMA(1, 0, At, B0); PG8_MMA(1, 1, At, B1); PG8_BAR; PG8_SCHED;
	s_add_i32 s36, s42, s50
	v_lshl_add_u64 v[218:219], v[218:219], 0, s[20:21]
	s_mov_b32 m0, s36
	ds_read_b128 v[180:183], v216 offset:49152
	ds_read_b128 v[184:187], v216 offset:50176
	ds_read_b128 v[188:191], v216 offset:51200
	ds_read_b128 v[192:195], v216 offset:52224
	ds_read_b128 v[196:199], v216 offset:53248
	ds_read_b128 v[200:203], v216 offset:54272
	ds_read_b128 v[204:207], v216 offset:55296
	ds_read_b128 v[208:211], v216 offset:56320
	global_load_lds_dwordx4 v[218:219], off
	s_add_i32 m0, s36, 0x2000
	s_add_u32 s6, s6, 0x40080
	v_lshl_add_u64 v[218:219], v[222:223], 0, s[20:21]
	s_addc_u32 s7, s7, 0
	s_add_i32 s36, s43, s50
	global_load_lds_dwordx4 v[218:219], off
	v_lshl_add_u64 v[218:219], s[6:7], 0, v[156:157]
	s_mov_b32 m0, s36
	s_nop 0
	global_load_lds_dwordx4 v[218:219], off
	v_lshl_add_u64 v[218:219], s[6:7], 0, v[160:161]
	s_add_i32 m0, s36, 0x2000
	s_nop 0
	global_load_lds_dwordx4 v[218:219], off
	v_lshl_add_u64 v[218:219], v[224:225], 0, s[20:21]
	s_mov_b32 m0, s63
	s_nop 0
	global_load_lds_dwordx4 v[218:219], off
	v_lshl_add_u64 v[218:219], v[226:227], 0, s[20:21]
	s_mov_b32 m0, s64
	s_nop 0
	global_load_lds_dwordx4 v[218:219], off
	s_waitcnt vmcnt(8)
	s_waitcnt lgkmcnt(0)
	s_barrier
	s_setprio 1
	s_waitcnt lgkmcnt(0)
	v_mfma_f32_16x16x32_bf16 v[78:81], v[58:61], v[180:183], v[78:81]
	v_mfma_f32_16x16x32_bf16 v[74:77], v[66:69], v[180:183], v[74:77]
	v_mfma_f32_16x16x32_bf16 v[46:49], v[58:61], v[188:191], v[46:49]
	v_mfma_f32_16x16x32_bf16 v[42:45], v[66:69], v[188:191], v[42:45]
	v_mfma_f32_16x16x32_bf16 v[30:33], v[58:61], v[196:199], v[30:33]
	v_mfma_f32_16x16x32_bf16 v[26:29], v[66:69], v[196:199], v[26:29]
	v_mfma_f32_16x16x32_bf16 v[14:17], v[58:61], v[204:207], v[14:17]
	v_mfma_f32_16x16x32_bf16 v[10:13], v[66:69], v[204:207], v[10:13]
	v_mfma_f32_16x16x32_bf16 v[78:81], v[62:65], v[184:187], v[78:81]
	v_mfma_f32_16x16x32_bf16 v[74:77], v[70:73], v[184:187], v[74:77]
	v_mfma_f32_16x16x32_bf16 v[46:49], v[62:65], v[192:195], v[46:49]
	v_mfma_f32_16x16x32_bf16 v[42:45], v[70:73], v[192:195], v[42:45]
	v_mfma_f32_16x16x32_bf16 v[30:33], v[62:65], v[200:203], v[30:33]
	v_mfma_f32_16x16x32_bf16 v[26:29], v[70:73], v[200:203], v[26:29]
	v_mfma_f32_16x16x32_bf16 v[14:17], v[62:65], v[208:211], v[14:17]
	v_mfma_f32_16x16x32_bf16 v[10:13], v[70:73], v[208:211], v[10:13]
	s_setprio 0
	s_setprio 1
	v_mfma_f32_16x16x32_bf16 v[50:53], v[146:149], v[180:183], v[50:53]
	v_mfma_f32_16x16x32_bf16 v[62:65], v[150:153], v[184:187], v[50:53]
	v_mfma_f32_16x16x32_bf16 v[50:53], v[172:175], v[180:183], v[54:57]
	v_mfma_f32_16x16x32_bf16 v[38:41], v[146:149], v[188:191], v[38:41]
	v_mfma_f32_16x16x32_bf16 v[34:37], v[172:175], v[188:191], v[34:37]
	v_mfma_f32_16x16x32_bf16 v[22:25], v[146:149], v[196:199], v[22:25]
	v_mfma_f32_16x16x32_bf16 v[18:21], v[172:175], v[196:199], v[18:21]
	v_mfma_f32_16x16x32_bf16 v[6:9], v[146:149], v[204:207], v[6:9]
	v_mfma_f32_16x16x32_bf16 v[2:5], v[172:175], v[204:207], v[2:5]
	v_mfma_f32_16x16x32_bf16 v[58:61], v[176:179], v[184:187], v[50:53]
	v_mfma_f32_16x16x32_bf16 v[38:41], v[150:153], v[192:195], v[38:41]
	v_mfma_f32_16x16x32_bf16 v[34:37], v[176:179], v[192:195], v[34:37]
	v_mfma_f32_16x16x32_bf16 v[22:25], v[150:153], v[200:203], v[22:25]
	v_mfma_f32_16x16x32_bf16 v[18:21], v[176:179], v[200:203], v[18:21]
	v_mfma_f32_16x16x32_bf16 v[6:9], v[150:153], v[208:211], v[6:9]
	v_mfma_f32_16x16x32_bf16 v[2:5], v[176:179], v[208:211], v[2:5]
	s_setprio 0
	s_add_i32 s41, s41, 2
	s_add_u32 s4, s4, 0x100
	s_addc_u32 s5, s5, 0
	s_add_u32 s39, s39, 0x100
	s_addc_u32 s40, s40, 0
	s_cmp_gt_u32 s41, 13
	s_cbranch_scc0 .Lrb3
	s_barrier
	s_and_b64 vcc, exec, s[22:23]
	s_cbranch_vccz .LBB0_841
	s_barrier

; #define PG8_STAGE(bufoff, gbase, voff) do { _Pragma("unroll") for (int _i = 0; _i < 2; ++_i) \
;         __builtin_amdgcn_global_load_lds((const unsigned*)((const char*)(gbase) + (voff)[_i]), (PG8_LAS unsigned*)(lds + (bufoff) + ldsw + _i * 8192), 16, 0, 0); } while (0)
; #define PG8_LDA(dst, b, h) do { _Pragma("unroll") for (int m = 0; m < 4; ++m) _Pragma("unroll") for (int k = 0; k < 2; ++k) dst[m][k] = *(const PG8_LAS bf16x8*)(lds + PG8_SA(b, h) + aoff + m * 2048 + k * 1024); } while (0)
; #define PG8_LDB(dst, b, h) do { _Pragma("unroll") for (int n = 0; n < 2; ++n) _Pragma("unroll") for (int k = 0; k < 2; ++k) dst[n][k] = *(const PG8_LAS bf16x8*)(lds + PG8_SB(b, h) + boff + n * 2048 + k * 1024); } while (0)
; #define PG8_MMA(ai, bj, At, Bt) do { __builtin_amdgcn_s_setprio(1); _Pragma("unroll") for (int m = 0; m < 4; ++m) _Pragma("unroll") for (int n = 0; n < 2; ++n) _Pragma("unroll") for (int k = 0; k < 2; ++k) \
;         acc[ai][bj][m][n] = __builtin_amdgcn_mfma_f32_16x16x32_bf16(Bt[n][k], At[m][k], acc[ai][bj][m][n], 0, 0, 0); __builtin_amdgcn_s_setprio(0); } while (0)
; #define PG8_WAIT_V(n) asm volatile("s_waitcnt vmcnt(" #n ")" ::: "memory")
; #define PG8_WAIT_L(n) asm volatile("s_waitcnt lgkmcnt(" #n ")" ::: "memory")
; #define PG8_BAR __builtin_amdgcn_s_barrier()
; #define PG8_SCHED __builtin_amdgcn_sched_barrier(0)
; template <class Epi, class Sched, bool ALIGN_EPI = false, bool SP2 = false>
; __device__ __forceinline__ void gemm_phase(PG8_LAS unsigned char* lds, const Gemm g, const Sched& S, const Epi& E) {
;     ...
;             PG8_LDB(B0, 1, 0); PG8_LDB(B1, 1, 1); PG8_SCHED; PG8_LDA(At, 1, 0); PG8_STAGE(PG8_SA(0, 1), a2 + hstep, voffA);
;             PG8_WAIT_V(8); PG8_WAIT_L(0); PG8_BAR; PG8_MMA(0, 0, At, B0); PG8_MMA(0, 1, At, B1); PG8_BAR; PG8_SCHED;
.Lpz5_mid:
	s_add_i32 s84, 0, 0x18000
	v_add_u32_e32 v130, s84, v193
	s_add_i32 s85, 0, 0x1c000
	ds_read_b128 v[138:141], v130
	ds_read_b128 v[142:145], v130 offset:1024
	ds_read_b128 v[146:149], v130 offset:2048
	ds_read_b128 v[150:153], v130 offset:3072
	v_add_u32_e32 v130, s85, v193
	ds_read_b128 v[154:157], v130
	ds_read_b128 v[158:161], v130 offset:1024
	ds_read_b128 v[162:165], v130 offset:2048
	ds_read_b128 v[166:169], v130 offset:3072
	s_add_u32 s44, s44, 0x40000
	s_addc_u32 s45, s45, 0
	s_mov_b32 m0, s60
	v_lshl_add_u64 v[130:131], s[44:45], 0, v[176:177]
	ds_read_b128 v[200:203], v197 offset:32768
	ds_read_b128 v[204:207], v197 offset:33792
	ds_read_b128 v[208:211], v197 offset:34816
	ds_read_b128 v[212:215], v197 offset:35840
	ds_read_b128 v[216:219], v197 offset:36864
	ds_read_b128 v[220:223], v197 offset:37888
	ds_read_b128 v[224:227], v197 offset:38912
	ds_read_b128 v[228:231], v197 offset:39936
	global_load_lds_dwordx4 v[130:131], off
	v_lshl_add_u64 v[130:131], s[44:45], 0, v[172:173]
	s_mov_b32 m0, s61
	s_nop 0
	global_load_lds_dwordx4 v[130:131], off
	s_waitcnt vmcnt(8)
	s_waitcnt lgkmcnt(0)
	s_barrier
	s_setprio 1
	s_waitcnt lgkmcnt(0)
	v_mfma_f32_16x16x32_bf16 v[98:101], v[138:141], v[200:203], v[98:101]
	v_mfma_f32_16x16x32_bf16 v[134:137], v[142:145], v[204:207], v[98:101]
	v_mfma_f32_16x16x32_bf16 v[98:101], v[146:149], v[200:203], v[106:109]
	v_mfma_f32_16x16x32_bf16 v[130:133], v[150:153], v[204:207], v[98:101]
	v_mfma_f32_16x16x32_bf16 v[98:101], v[138:141], v[208:211], v[118:121]
	v_mfma_f32_16x16x32_bf16 v[118:121], v[142:145], v[212:215], v[98:101]
	v_mfma_f32_16x16x32_bf16 v[98:101], v[146:149], v[208:211], v[114:117]
	v_mfma_f32_16x16x32_bf16 v[94:97], v[138:141], v[216:219], v[94:97]
	v_mfma_f32_16x16x32_bf16 v[90:93], v[146:149], v[216:219], v[90:93]
	v_mfma_f32_16x16x32_bf16 v[78:81], v[138:141], v[224:227], v[78:81]
	v_mfma_f32_16x16x32_bf16 v[74:77], v[146:149], v[224:227], v[74:77]
	v_mfma_f32_16x16x32_bf16 v[114:117], v[150:153], v[212:215], v[98:101]
	v_mfma_f32_16x16x32_bf16 v[94:97], v[142:145], v[220:223], v[94:97]
	v_mfma_f32_16x16x32_bf16 v[90:93], v[150:153], v[220:223], v[90:93]
	v_mfma_f32_16x16x32_bf16 v[78:81], v[142:145], v[228:231], v[78:81]
	v_mfma_f32_16x16x32_bf16 v[74:77], v[150:153], v[228:231], v[74:77]
	s_setprio 0
	s_setprio 1
	v_mfma_f32_16x16x32_bf16 v[98:101], v[154:157], v[200:203], v[126:129]
	v_mfma_f32_16x16x32_bf16 v[126:129], v[158:161], v[204:207], v[98:101]
	v_mfma_f32_16x16x32_bf16 v[98:101], v[162:165], v[200:203], v[122:125]
	v_mfma_f32_16x16x32_bf16 v[122:125], v[166:169], v[204:207], v[98:101]
	v_mfma_f32_16x16x32_bf16 v[98:101], v[154:157], v[208:211], v[110:113]
	v_mfma_f32_16x16x32_bf16 v[110:113], v[158:161], v[212:215], v[98:101]
	v_mfma_f32_16x16x32_bf16 v[98:101], v[162:165], v[208:211], v[102:105]
	v_mfma_f32_16x16x32_bf16 v[86:89], v[154:157], v[216:219], v[86:89]
	v_mfma_f32_16x16x32_bf16 v[82:85], v[162:165], v[216:219], v[82:85]
	v_mfma_f32_16x16x32_bf16 v[70:73], v[154:157], v[224:227], v[70:73]
	v_mfma_f32_16x16x32_bf16 v[66:69], v[162:165], v[224:227], v[66:69]
	v_mfma_f32_16x16x32_bf16 v[102:105], v[166:169], v[212:215], v[98:101]
	v_mfma_f32_16x16x32_bf16 v[86:89], v[158:161], v[220:223], v[86:89]
	v_mfma_f32_16x16x32_bf16 v[82:85], v[166:169], v[220:223], v[82:85]
	v_mfma_f32_16x16x32_bf16 v[70:73], v[158:161], v[228:231], v[70:73]
	v_mfma_f32_16x16x32_bf16 v[66:69], v[166:169], v[228:231], v[66:69]
	s_setprio 0
	s_barrier
; #define PG8_STAGE(bufoff, gbase, voff) do { _Pragma("unroll") for (int _i = 0; _i < 2; ++_i) \
;         __builtin_amdgcn_global_load_lds((const unsigned*)((const char*)(gbase) + (voff)[_i]), (PG8_LAS unsigned*)(lds + (bufoff) + ldsw + _i * 8192), 16, 0, 0); } while (0)
; #define PG8_LDA(dst, b, h) do { _Pragma("unroll") for (int m = 0; m < 4; ++m) _Pragma("unroll") for (int k = 0; k < 2; ++k) dst[m][k] = *(const PG8_LAS bf16x8*)(lds + PG8_SA(b, h) + aoff + m * 2048 + k * 1024); } while (0)
; #define PG8_MMA(ai, bj, At, Bt) do { __builtin_amdgcn_s_setprio(1); _Pragma("unroll") for (int m = 0; m < 4; ++m) _Pragma("unroll") for (int n = 0; n < 2; ++n) _Pragma("unroll") for (int k = 0; k < 2; ++k) \
;         acc[ai][bj][m][n] = __builtin_amdgcn_mfma_f32_16x16x32_bf16(Bt[n][k], At[m][k], acc[ai][bj][m][n], 0, 0, 0); __builtin_amdgcn_s_setprio(0); } while (0)
; #define PG8_WAIT_V(n) asm volatile("s_waitcnt vmcnt(" #n ")" ::: "memory")
; #define PG8_WAIT_L(n) asm volatile("s_waitcnt lgkmcnt(" #n ")" ::: "memory")
; #define PG8_BAR __builtin_amdgcn_s_barrier()
; #define PG8_SCHED __builtin_amdgcn_sched_barrier(0)
; template <class Epi, class Sched, bool ALIGN_EPI = false, bool SP2 = false>
; __device__ __forceinline__ void gemm_phase(PG8_LAS unsigned char* lds, const Gemm g, const Sched& S, const Epi& E) {
;     ...
;         for (int t = 0; t < nt; t += 2) {
;             const bool last = (t == nt - 2);
;     ...
;             PG8_LDA(At, 1, 1); PG8_STAGE(PG8_SB(1, 0), b3, voffB); PG8_STAGE(PG8_SB(1, 1), b3 + hstep, voffB); PG8_STAGE(PG8_SA(1, 0), a3, voffA);
;             PG8_WAIT_V(8); PG8_WAIT_L(0); PG8_BAR; PG8_MMA(1, 0, At, B0); PG8_MMA(1, 1, At, B1); PG8_BAR; PG8_SCHED;
	s_add_i32 s44, s84, s51
	v_lshl_add_u64 v[224:225], v[232:233], 0, s[8:9]
	s_mov_b32 m0, s44
	ds_read_b128 v[98:101], v197 offset:49152
	ds_read_b128 v[106:109], v197 offset:50176
	ds_read_b128 v[200:203], v197 offset:51200
	ds_read_b128 v[204:207], v197 offset:52224
	ds_read_b128 v[208:211], v197 offset:53248
	ds_read_b128 v[212:215], v197 offset:54272
	ds_read_b128 v[216:219], v197 offset:55296
	ds_read_b128 v[220:223], v197 offset:56320
	global_load_lds_dwordx4 v[224:225], off
	s_add_i32 m0, s44, 0x2000
	s_add_u32 s42, s42, 0x40080
	v_lshl_add_u64 v[224:225], v[234:235], 0, s[8:9]
	s_addc_u32 s43, s43, 0
	s_add_i32 s44, s85, s51
	global_load_lds_dwordx4 v[224:225], off
	v_lshl_add_u64 v[224:225], s[42:43], 0, v[174:175]
	s_mov_b32 m0, s44
	s_nop 0
	global_load_lds_dwordx4 v[224:225], off
	v_lshl_add_u64 v[224:225], s[42:43], 0, v[170:171]
	s_add_i32 m0, s44, 0x2000
	s_nop 0
	global_load_lds_dwordx4 v[224:225], off
	v_lshl_add_u64 v[224:225], v[236:237], 0, s[8:9]
	s_mov_b32 m0, s65
	s_nop 0
	global_load_lds_dwordx4 v[224:225], off
	v_lshl_add_u64 v[224:225], v[238:239], 0, s[8:9]
	s_mov_b32 m0, s66
	s_nop 0
	global_load_lds_dwordx4 v[224:225], off
	s_waitcnt vmcnt(8)
	s_waitcnt lgkmcnt(0)
	s_barrier
	s_setprio 1
	s_waitcnt lgkmcnt(0)
	v_mfma_f32_16x16x32_bf16 v[62:65], v[138:141], v[98:101], v[62:65]
	v_mfma_f32_16x16x32_bf16 v[58:61], v[146:149], v[98:101], v[58:61]
	v_mfma_f32_16x16x32_bf16 v[46:49], v[138:141], v[200:203], v[46:49]
	v_mfma_f32_16x16x32_bf16 v[42:45], v[146:149], v[200:203], v[42:45]
	v_mfma_f32_16x16x32_bf16 v[30:33], v[138:141], v[208:211], v[30:33]
	v_mfma_f32_16x16x32_bf16 v[26:29], v[146:149], v[208:211], v[26:29]
	v_mfma_f32_16x16x32_bf16 v[14:17], v[138:141], v[216:219], v[14:17]
	v_mfma_f32_16x16x32_bf16 v[10:13], v[146:149], v[216:219], v[10:13]
	v_mfma_f32_16x16x32_bf16 v[62:65], v[142:145], v[106:109], v[62:65]
	v_mfma_f32_16x16x32_bf16 v[58:61], v[150:153], v[106:109], v[58:61]
	v_mfma_f32_16x16x32_bf16 v[46:49], v[142:145], v[204:207], v[46:49]
	v_mfma_f32_16x16x32_bf16 v[42:45], v[150:153], v[204:207], v[42:45]
	v_mfma_f32_16x16x32_bf16 v[30:33], v[142:145], v[212:215], v[30:33]
	v_mfma_f32_16x16x32_bf16 v[26:29], v[150:153], v[212:215], v[26:29]
	v_mfma_f32_16x16x32_bf16 v[14:17], v[142:145], v[220:223], v[14:17]
	v_mfma_f32_16x16x32_bf16 v[10:13], v[150:153], v[220:223], v[10:13]
	s_setprio 0
	s_setprio 1
	v_mfma_f32_16x16x32_bf16 v[54:57], v[154:157], v[98:101], v[54:57]
	v_mfma_f32_16x16x32_bf16 v[50:53], v[162:165], v[98:101], v[50:53]
	v_mfma_f32_16x16x32_bf16 v[38:41], v[154:157], v[200:203], v[38:41]
	v_mfma_f32_16x16x32_bf16 v[34:37], v[162:165], v[200:203], v[34:37]
	v_mfma_f32_16x16x32_bf16 v[22:25], v[154:157], v[208:211], v[22:25]
	v_mfma_f32_16x16x32_bf16 v[18:21], v[162:165], v[208:211], v[18:21]
	v_mfma_f32_16x16x32_bf16 v[6:9], v[154:157], v[216:219], v[6:9]
	v_mfma_f32_16x16x32_bf16 v[2:5], v[162:165], v[216:219], v[2:5]
	v_mfma_f32_16x16x32_bf16 v[54:57], v[158:161], v[106:109], v[54:57]
	v_mfma_f32_16x16x32_bf16 v[50:53], v[166:169], v[106:109], v[50:53]
	v_mfma_f32_16x16x32_bf16 v[38:41], v[158:161], v[204:207], v[38:41]
	v_mfma_f32_16x16x32_bf16 v[34:37], v[166:169], v[204:207], v[34:37]
	v_mfma_f32_16x16x32_bf16 v[22:25], v[158:161], v[212:215], v[22:25]
	v_mfma_f32_16x16x32_bf16 v[18:21], v[166:169], v[212:215], v[18:21]
	v_mfma_f32_16x16x32_bf16 v[6:9], v[158:161], v[220:223], v[6:9]
	v_mfma_f32_16x16x32_bf16 v[2:5], v[166:169], v[220:223], v[2:5]
	s_setprio 0
	s_add_i32 s42, s83, 2
	s_add_u32 s40, s40, 0x100
	s_addc_u32 s41, s41, 0
	s_cmp_gt_u32 s83, 13
	s_mov_b32 s83, s42
	s_cbranch_scc1 .Lrx2
	s_barrier

; #define PG8_STAGE(bufoff, gbase, voff) do { _Pragma("unroll") for (int _i = 0; _i < 2; ++_i) \
;         __builtin_amdgcn_global_load_lds((const unsigned*)((const char*)(gbase) + (voff)[_i]), (PG8_LAS unsigned*)(lds + (bufoff) + ldsw + _i * 8192), 16, 0, 0); } while (0)
; #define PG8_LDA(dst, b, h) do { _Pragma("unroll") for (int m = 0; m < 4; ++m) _Pragma("unroll") for (int k = 0; k < 2; ++k) dst[m][k] = *(const PG8_LAS bf16x8*)(lds + PG8_SA(b, h) + aoff + m * 2048 + k * 1024); } while (0)
; #define PG8_LDB(dst, b, h) do { _Pragma("unroll") for (int n = 0; n < 2; ++n) _Pragma("unroll") for (int k = 0; k < 2; ++k) dst[n][k] = *(const PG8_LAS bf16x8*)(lds + PG8_SB(b, h) + boff + n * 2048 + k * 1024); } while (0)
; #define PG8_MMA(ai, bj, At, Bt) do { __builtin_amdgcn_s_setprio(1); _Pragma("unroll") for (int m = 0; m < 4; ++m) _Pragma("unroll") for (int n = 0; n < 2; ++n) _Pragma("unroll") for (int k = 0; k < 2; ++k) \
;         acc[ai][bj][m][n] = __builtin_amdgcn_mfma_f32_16x16x32_bf16(Bt[n][k], At[m][k], acc[ai][bj][m][n], 0, 0, 0); __builtin_amdgcn_s_setprio(0); } while (0)
; #define PG8_WAIT_V(n) asm volatile("s_waitcnt vmcnt(" #n ")" ::: "memory")
; #define PG8_WAIT_L(n) asm volatile("s_waitcnt lgkmcnt(" #n ")" ::: "memory")
; #define PG8_BAR __builtin_amdgcn_s_barrier()
; #define PG8_SCHED __builtin_amdgcn_sched_barrier(0)
; template <class Epi, class Sched, bool ALIGN_EPI = false, bool SP2 = false>
; __device__ __forceinline__ void gemm_phase(PG8_LAS unsigned char* lds, const Gemm g, const Sched& S, const Epi& E) {
;     ...
;             PG8_LDB(B0, 1, 0); PG8_LDB(B1, 1, 1); PG8_SCHED; PG8_LDA(At, 1, 0); PG8_STAGE(PG8_SA(0, 1), a2 + hstep, voffA);
;             PG8_WAIT_V(8); PG8_WAIT_L(0); PG8_BAR; PG8_MMA(0, 0, At, B0); PG8_MMA(0, 1, At, B1); PG8_BAR; PG8_SCHED;
.Lpz6_mid:
	s_add_i32 s38, 0, 0x18000
	v_add_u32_e32 v146, s38, v191
	s_add_i32 s39, 0, 0x1c000
	ds_read_b128 v[130:133], v146
	ds_read_b128 v[134:137], v146 offset:1024
	ds_read_b128 v[156:159], v146 offset:2048
	ds_read_b128 v[160:163], v146 offset:3072
	v_add_u32_e32 v146, s39, v191
	ds_read_b128 v[164:167], v146
	ds_read_b128 v[168:171], v146 offset:1024
	ds_read_b128 v[172:175], v146 offset:2048
	ds_read_b128 v[176:179], v146 offset:3072
	s_add_u32 s4, s30, 0xb0000
	s_addc_u32 s5, s31, 0
	s_mov_b32 m0, s47
	v_lshl_add_u64 v[226:227], s[4:5], 0, v[138:139]
	ds_read_b128 v[180:183], v194 offset:32768
	ds_read_b128 v[184:187], v194 offset:33792
	ds_read_b128 v[196:199], v194 offset:34816
	ds_read_b128 v[200:203], v194 offset:35840
	ds_read_b128 v[204:207], v194 offset:36864
	ds_read_b128 v[208:211], v194 offset:37888
	ds_read_b128 v[212:215], v194 offset:38912
	ds_read_b128 v[216:219], v194 offset:39936
	global_load_lds_dwordx4 v[226:227], off
	v_lshl_add_u64 v[226:227], s[4:5], 0, v[142:143]
	s_mov_b32 m0, s48
	s_nop 0
	global_load_lds_dwordx4 v[226:227], off
	s_waitcnt vmcnt(8)
	s_waitcnt lgkmcnt(0)
	s_barrier
	s_setprio 1
	s_waitcnt lgkmcnt(0)
	v_mfma_f32_16x16x32_bf16 v[126:129], v[130:133], v[180:183], v[126:129]
	v_mfma_f32_16x16x32_bf16 v[122:125], v[156:159], v[180:183], v[122:125]
	v_mfma_f32_16x16x32_bf16 v[110:113], v[130:133], v[196:199], v[110:113]
	v_mfma_f32_16x16x32_bf16 v[106:109], v[156:159], v[196:199], v[106:109]
	v_mfma_f32_16x16x32_bf16 v[94:97], v[130:133], v[204:207], v[94:97]
	v_mfma_f32_16x16x32_bf16 v[90:93], v[156:159], v[204:207], v[90:93]
	v_mfma_f32_16x16x32_bf16 v[78:81], v[130:133], v[212:215], v[78:81]
	v_mfma_f32_16x16x32_bf16 v[74:77], v[156:159], v[212:215], v[74:77]
	v_mfma_f32_16x16x32_bf16 v[126:129], v[134:137], v[184:187], v[126:129]
	v_mfma_f32_16x16x32_bf16 v[122:125], v[160:163], v[184:187], v[122:125]
	v_mfma_f32_16x16x32_bf16 v[110:113], v[134:137], v[200:203], v[110:113]
	v_mfma_f32_16x16x32_bf16 v[106:109], v[160:163], v[200:203], v[106:109]
	v_mfma_f32_16x16x32_bf16 v[94:97], v[134:137], v[208:211], v[94:97]
	v_mfma_f32_16x16x32_bf16 v[90:93], v[160:163], v[208:211], v[90:93]
	v_mfma_f32_16x16x32_bf16 v[78:81], v[134:137], v[216:219], v[78:81]
	v_mfma_f32_16x16x32_bf16 v[74:77], v[160:163], v[216:219], v[74:77]
	s_setprio 0
	s_setprio 1
	v_mfma_f32_16x16x32_bf16 v[118:121], v[164:167], v[180:183], v[118:121]
	v_mfma_f32_16x16x32_bf16 v[114:117], v[172:175], v[180:183], v[114:117]
	v_mfma_f32_16x16x32_bf16 v[102:105], v[164:167], v[196:199], v[102:105]
	v_mfma_f32_16x16x32_bf16 v[98:101], v[172:175], v[196:199], v[98:101]
	v_mfma_f32_16x16x32_bf16 v[86:89], v[164:167], v[204:207], v[86:89]
	v_mfma_f32_16x16x32_bf16 v[82:85], v[172:175], v[204:207], v[82:85]
	v_mfma_f32_16x16x32_bf16 v[70:73], v[164:167], v[212:215], v[70:73]
	v_mfma_f32_16x16x32_bf16 v[66:69], v[172:175], v[212:215], v[66:69]
	v_mfma_f32_16x16x32_bf16 v[118:121], v[168:171], v[184:187], v[118:121]
	v_mfma_f32_16x16x32_bf16 v[114:117], v[176:179], v[184:187], v[114:117]
	v_mfma_f32_16x16x32_bf16 v[102:105], v[168:171], v[200:203], v[102:105]
	v_mfma_f32_16x16x32_bf16 v[98:101], v[176:179], v[200:203], v[98:101]
	v_mfma_f32_16x16x32_bf16 v[86:89], v[168:171], v[208:211], v[86:89]
	v_mfma_f32_16x16x32_bf16 v[82:85], v[176:179], v[208:211], v[82:85]
	v_mfma_f32_16x16x32_bf16 v[70:73], v[168:171], v[216:219], v[70:73]
	v_mfma_f32_16x16x32_bf16 v[66:69], v[176:179], v[216:219], v[66:69]
	s_setprio 0
	s_barrier
; #define PG8_STAGE(bufoff, gbase, voff) do { _Pragma("unroll") for (int _i = 0; _i < 2; ++_i) \
;         __builtin_amdgcn_global_load_lds((const unsigned*)((const char*)(gbase) + (voff)[_i]), (PG8_LAS unsigned*)(lds + (bufoff) + ldsw + _i * 8192), 16, 0, 0); } while (0)
; #define PG8_LDA(dst, b, h) do { _Pragma("unroll") for (int m = 0; m < 4; ++m) _Pragma("unroll") for (int k = 0; k < 2; ++k) dst[m][k] = *(const PG8_LAS bf16x8*)(lds + PG8_SA(b, h) + aoff + m * 2048 + k * 1024); } while (0)
; #define PG8_MMA(ai, bj, At, Bt) do { __builtin_amdgcn_s_setprio(1); _Pragma("unroll") for (int m = 0; m < 4; ++m) _Pragma("unroll") for (int n = 0; n < 2; ++n) _Pragma("unroll") for (int k = 0; k < 2; ++k) \
;         acc[ai][bj][m][n] = __builtin_amdgcn_mfma_f32_16x16x32_bf16(Bt[n][k], At[m][k], acc[ai][bj][m][n], 0, 0, 0); __builtin_amdgcn_s_setprio(0); } while (0)
; #define PG8_WAIT_V(n) asm volatile("s_waitcnt vmcnt(" #n ")" ::: "memory")
; #define PG8_WAIT_L(n) asm volatile("s_waitcnt lgkmcnt(" #n ")" ::: "memory")
; #define PG8_BAR __builtin_amdgcn_s_barrier()
; #define PG8_SCHED __builtin_amdgcn_sched_barrier(0)
; template <class Epi, class Sched, bool ALIGN_EPI = false, bool SP2 = false>
; __device__ __forceinline__ void gemm_phase(PG8_LAS unsigned char* lds, const Gemm g, const Sched& S, const Epi& E) {
;     ...
;         for (int t = 0; t < nt; t += 2) {
;             const bool last = (t == nt - 2);
;     ...
;             PG8_LDA(At, 1, 1); PG8_STAGE(PG8_SB(1, 0), b3, voffB); PG8_STAGE(PG8_SB(1, 1), b3 + hstep, voffB); PG8_STAGE(PG8_SA(1, 0), a3, voffA);
;             PG8_WAIT_V(8); PG8_WAIT_L(0); PG8_BAR; PG8_MMA(1, 0, At, B0); PG8_MMA(1, 1, At, B1); PG8_BAR; PG8_SCHED;
	s_add_i32 s4, s38, s44
	v_lshl_add_u64 v[188:189], v[188:189], 0, s[18:19]
	s_mov_b32 m0, s4
	ds_read_b128 v[180:183], v194 offset:49152
	ds_read_b128 v[184:187], v194 offset:50176
	ds_read_b128 v[196:199], v194 offset:51200
	ds_read_b128 v[200:203], v194 offset:52224
	ds_read_b128 v[204:207], v194 offset:53248
	ds_read_b128 v[208:211], v194 offset:54272
	ds_read_b128 v[212:215], v194 offset:55296
	ds_read_b128 v[216:219], v194 offset:56320
	global_load_lds_dwordx4 v[188:189], off
	s_add_i32 m0, s4, 0x2000
	s_add_u32 s4, s6, 0xb0080
	v_lshl_add_u64 v[188:189], v[220:221], 0, s[18:19]
	s_addc_u32 s5, s7, 0
	s_add_i32 s6, s39, s44
	global_load_lds_dwordx4 v[188:189], off
	v_lshl_add_u64 v[188:189], s[4:5], 0, v[140:141]
	s_mov_b32 m0, s6
	s_nop 0
	global_load_lds_dwordx4 v[188:189], off
	v_lshl_add_u64 v[188:189], s[4:5], 0, v[144:145]
	s_add_i32 m0, s6, 0x2000
	s_nop 0
	global_load_lds_dwordx4 v[188:189], off
	v_lshl_add_u64 v[188:189], v[222:223], 0, s[20:21]
	s_mov_b32 m0, s55
	s_nop 0
	global_load_lds_dwordx4 v[188:189], off
	v_lshl_add_u64 v[188:189], v[224:225], 0, s[20:21]
	s_mov_b32 m0, s56
	s_nop 0
	global_load_lds_dwordx4 v[188:189], off
	s_waitcnt vmcnt(8)
	s_waitcnt lgkmcnt(0)
	s_barrier
	s_setprio 1
	s_waitcnt lgkmcnt(0)
	v_mfma_f32_16x16x32_bf16 v[62:65], v[130:133], v[180:183], v[62:65]
	v_mfma_f32_16x16x32_bf16 v[58:61], v[156:159], v[180:183], v[58:61]
	v_mfma_f32_16x16x32_bf16 v[46:49], v[130:133], v[196:199], v[46:49]
	v_mfma_f32_16x16x32_bf16 v[42:45], v[156:159], v[196:199], v[42:45]
	v_mfma_f32_16x16x32_bf16 v[30:33], v[130:133], v[204:207], v[30:33]
	v_mfma_f32_16x16x32_bf16 v[26:29], v[156:159], v[204:207], v[26:29]
	v_mfma_f32_16x16x32_bf16 v[14:17], v[130:133], v[212:215], v[14:17]
	v_mfma_f32_16x16x32_bf16 v[10:13], v[156:159], v[212:215], v[10:13]
	v_mfma_f32_16x16x32_bf16 v[62:65], v[134:137], v[184:187], v[62:65]
	v_mfma_f32_16x16x32_bf16 v[58:61], v[160:163], v[184:187], v[58:61]
	v_mfma_f32_16x16x32_bf16 v[46:49], v[134:137], v[200:203], v[46:49]
	v_mfma_f32_16x16x32_bf16 v[42:45], v[160:163], v[200:203], v[42:45]
	v_mfma_f32_16x16x32_bf16 v[30:33], v[134:137], v[208:211], v[30:33]
	v_mfma_f32_16x16x32_bf16 v[26:29], v[160:163], v[208:211], v[26:29]
	v_mfma_f32_16x16x32_bf16 v[14:17], v[134:137], v[216:219], v[14:17]
	v_mfma_f32_16x16x32_bf16 v[10:13], v[160:163], v[216:219], v[10:13]
	s_setprio 0
	s_setprio 1
	v_mfma_f32_16x16x32_bf16 v[54:57], v[164:167], v[180:183], v[54:57]
	v_mfma_f32_16x16x32_bf16 v[50:53], v[172:175], v[180:183], v[50:53]
	v_mfma_f32_16x16x32_bf16 v[38:41], v[164:167], v[196:199], v[38:41]
	v_mfma_f32_16x16x32_bf16 v[34:37], v[172:175], v[196:199], v[34:37]
	v_mfma_f32_16x16x32_bf16 v[22:25], v[164:167], v[204:207], v[22:25]
	v_mfma_f32_16x16x32_bf16 v[18:21], v[172:175], v[204:207], v[18:21]
	v_mfma_f32_16x16x32_bf16 v[6:9], v[164:167], v[212:215], v[6:9]
	v_mfma_f32_16x16x32_bf16 v[2:5], v[172:175], v[212:215], v[2:5]
	v_mfma_f32_16x16x32_bf16 v[54:57], v[168:171], v[184:187], v[54:57]
	v_mfma_f32_16x16x32_bf16 v[50:53], v[176:179], v[184:187], v[50:53]
	v_mfma_f32_16x16x32_bf16 v[38:41], v[168:171], v[200:203], v[38:41]
	v_mfma_f32_16x16x32_bf16 v[34:37], v[176:179], v[200:203], v[34:37]
	v_mfma_f32_16x16x32_bf16 v[22:25], v[168:171], v[208:211], v[22:25]
	v_mfma_f32_16x16x32_bf16 v[18:21], v[176:179], v[208:211], v[18:21]
	v_mfma_f32_16x16x32_bf16 v[6:9], v[168:171], v[216:219], v[6:9]
	v_mfma_f32_16x16x32_bf16 v[2:5], v[176:179], v[216:219], v[2:5]
	s_setprio 0
	s_add_i32 s37, s37, 2
	s_add_u32 s35, s35, 0x100
	s_addc_u32 s36, s36, 0
	s_cmp_gt_u32 s37, 41
	s_mov_b64 s[4:5], s[0:1]
	s_cbranch_scc0 .Lrb4
	s_barrier
	s_and_b64 vcc, exec, s[22:23]
	s_cbranch_vccz .LBB0_1072
	s_barrier
